# GEMM K-loops: LDS-DMA loads use SGPR-base + 32-bit VGPR offset form instead of a VALU 64-bit add per load (33 of 80 sites)
# speedup vs baseline: 1.0928x; 1.0047x over previous
.LBB0_42:
	s_add_u32 s8, s4, s2
	s_addc_u32 s9, s5, 0
	s_add_u32 s3, s8, 0x100
	s_addc_u32 s10, s9, 0
	s_and_b64 s[6:7], s[84:85], exec
	s_cselect_b32 s7, s87, s10
	s_cselect_b32 s6, s86, s3
	s_add_u32 s2, s36, s2
	s_addc_u32 s3, s37, 0
	s_add_u32 s10, s2, 0x100
	ds_read_b128 v[128:131], v221
	ds_read_b128 v[132:135], v222
	ds_read_b128 v[136:139], v223
	ds_read_b128 v[140:143], v224
	ds_read_b128 v[144:147], v225
	ds_read_b128 v[148:151], v226
	ds_read_b128 v[152:155], v227
	ds_read_b128 v[156:159], v228
	s_addc_u32 s11, s3, 0
	s_and_b64 s[2:3], s[84:85], exec
	s_cselect_b32 vcc_hi, s89, s11
	s_cselect_b32 vcc_lo, s88, s10
	s_add_u32 s10, s8, 0x30080
	s_addc_u32 s11, s9, 0
	s_add_u32 s8, vcc_lo, 0x10000
	s_addc_u32 s9, vcc_hi, 0
	s_add_u32 s2, s6, 0x30000
	s_addc_u32 s3, s7, 0
	s_add_u32 s84, vcc_lo, 0x10080
	s_addc_u32 s85, vcc_hi, 0
	s_mov_b32 m0, s19
	ds_read_b128 v[160:163], v219
	ds_read_b128 v[164:167], v219 offset:1024
	ds_read_b128 v[168:171], v219 offset:2048
	ds_read_b128 v[172:175], v219 offset:3072
	ds_read_b128 v[198:201], v219 offset:4096
	ds_read_b128 v[202:205], v219 offset:5120
	ds_read_b128 v[238:241], v219 offset:6144
	ds_read_b128 v[242:245], v219 offset:7168
	global_load_lds_dwordx4 v192, s[10:11]
	s_mov_b32 m0, s74
	s_nop 0
	global_load_lds_dwordx4 v188, s[10:11]
	s_waitcnt vmcnt(8)
	s_waitcnt lgkmcnt(0)
	s_barrier
	s_setprio 1
	s_waitcnt lgkmcnt(0)
	v_mfma_f32_16x16x32_bf16 v[104:107], v[128:131], v[160:163], v[104:107]
	v_mfma_f32_16x16x32_bf16 v[124:127], v[136:139], v[160:163], v[124:127]
	v_mfma_f32_16x16x32_bf16 v[96:99], v[128:131], v[168:171], v[96:99]
	v_mfma_f32_16x16x32_bf16 v[120:123], v[136:139], v[168:171], v[120:123]
	v_mfma_f32_16x16x32_bf16 v[88:91], v[128:131], v[198:201], v[88:91]
	v_mfma_f32_16x16x32_bf16 v[116:119], v[136:139], v[198:201], v[116:119]
	v_mfma_f32_16x16x32_bf16 v[80:83], v[128:131], v[238:241], v[80:83]
	v_mfma_f32_16x16x32_bf16 v[112:115], v[136:139], v[238:241], v[112:115]
	v_mfma_f32_16x16x32_bf16 v[104:107], v[132:135], v[164:167], v[104:107]
	v_mfma_f32_16x16x32_bf16 v[124:127], v[140:143], v[164:167], v[124:127]
	v_mfma_f32_16x16x32_bf16 v[96:99], v[132:135], v[172:175], v[96:99]
	v_mfma_f32_16x16x32_bf16 v[120:123], v[140:143], v[172:175], v[120:123]
	v_mfma_f32_16x16x32_bf16 v[88:91], v[132:135], v[202:205], v[88:91]
	v_mfma_f32_16x16x32_bf16 v[116:119], v[140:143], v[202:205], v[116:119]
	v_mfma_f32_16x16x32_bf16 v[80:83], v[132:135], v[242:245], v[80:83]
	v_mfma_f32_16x16x32_bf16 v[112:115], v[140:143], v[242:245], v[112:115]
	s_setprio 0
	s_setprio 1
	v_mfma_f32_16x16x32_bf16 v[72:75], v[144:147], v[160:163], v[72:75]
	v_mfma_f32_16x16x32_bf16 v[108:111], v[152:155], v[160:163], v[108:111]
	v_mfma_f32_16x16x32_bf16 v[64:67], v[144:147], v[168:171], v[64:67]
	v_mfma_f32_16x16x32_bf16 v[100:103], v[152:155], v[168:171], v[100:103]
	v_mfma_f32_16x16x32_bf16 v[56:59], v[144:147], v[198:201], v[56:59]
	v_mfma_f32_16x16x32_bf16 v[92:95], v[152:155], v[198:201], v[92:95]
	v_mfma_f32_16x16x32_bf16 v[48:51], v[144:147], v[238:241], v[48:51]
	v_mfma_f32_16x16x32_bf16 v[84:87], v[152:155], v[238:241], v[84:87]
	v_mfma_f32_16x16x32_bf16 v[72:75], v[148:151], v[164:167], v[72:75]
	v_mfma_f32_16x16x32_bf16 v[108:111], v[156:159], v[164:167], v[108:111]
	v_mfma_f32_16x16x32_bf16 v[64:67], v[148:151], v[172:175], v[64:67]
	v_mfma_f32_16x16x32_bf16 v[100:103], v[156:159], v[172:175], v[100:103]
	v_mfma_f32_16x16x32_bf16 v[56:59], v[148:151], v[202:205], v[56:59]
	v_mfma_f32_16x16x32_bf16 v[92:95], v[156:159], v[202:205], v[92:95]
	v_mfma_f32_16x16x32_bf16 v[48:51], v[148:151], v[242:245], v[48:51]
	v_mfma_f32_16x16x32_bf16 v[84:87], v[156:159], v[242:245], v[84:87]
	s_setprio 0
	s_barrier
	s_mov_b32 m0, s23
	v_lshl_add_u64 v[246:247], vcc, 0, v[190:191]
	ds_read_b128 v[160:163], v219 offset:16384
	ds_read_b128 v[164:167], v219 offset:17408
	ds_read_b128 v[168:171], v219 offset:18432
	ds_read_b128 v[172:175], v219 offset:19456
	ds_read_b128 v[198:201], v219 offset:20480
	ds_read_b128 v[202:205], v219 offset:21504
	ds_read_b128 v[238:241], v219 offset:22528
	ds_read_b128 v[242:245], v219 offset:23552
	global_load_lds_dwordx4 v[246:247], off
	v_lshl_add_u64 v[248:249], vcc, 0, v[186:187]
	s_mov_b32 m0, s91
	s_nop 0
	global_load_lds_dwordx4 v[248:249], off
	s_mov_b32 m0, s21
	v_lshl_add_u64 v[252:253], s[6:7], 0, v[188:189]
	global_load_lds_dwordx4 v190, s[8:9]
	s_mov_b32 m0, s27
	s_nop 0
	global_load_lds_dwordx4 v186, s[8:9]
	v_lshl_add_u64 v[250:251], s[6:7], 0, v[192:193]
	s_mov_b32 m0, s43
	s_nop 0
	global_load_lds_dwordx4 v[250:251], off
	s_mov_b32 m0, s26
	s_nop 0
	global_load_lds_dwordx4 v[252:253], off
	s_waitcnt vmcnt(8)
	s_waitcnt lgkmcnt(0)
	s_barrier
	s_setprio 1
	s_waitcnt lgkmcnt(0)
	v_mfma_f32_16x16x32_bf16 v[40:43], v[128:131], v[160:163], v[40:43]
	v_mfma_f32_16x16x32_bf16 v[76:79], v[136:139], v[160:163], v[76:79]
	v_mfma_f32_16x16x32_bf16 v[32:35], v[128:131], v[168:171], v[32:35]
	v_mfma_f32_16x16x32_bf16 v[68:71], v[136:139], v[168:171], v[68:71]
	v_mfma_f32_16x16x32_bf16 v[24:27], v[128:131], v[198:201], v[24:27]
	v_mfma_f32_16x16x32_bf16 v[60:63], v[136:139], v[198:201], v[60:63]
	v_mfma_f32_16x16x32_bf16 v[20:23], v[128:131], v[238:241], v[20:23]
	v_mfma_f32_16x16x32_bf16 v[52:55], v[136:139], v[238:241], v[52:55]
	v_mfma_f32_16x16x32_bf16 v[40:43], v[132:135], v[164:167], v[40:43]
	v_mfma_f32_16x16x32_bf16 v[76:79], v[140:143], v[164:167], v[76:79]
	v_mfma_f32_16x16x32_bf16 v[32:35], v[132:135], v[172:175], v[32:35]
	v_mfma_f32_16x16x32_bf16 v[68:71], v[140:143], v[172:175], v[68:71]
	v_mfma_f32_16x16x32_bf16 v[24:27], v[132:135], v[202:205], v[24:27]
	v_mfma_f32_16x16x32_bf16 v[60:63], v[140:143], v[202:205], v[60:63]
	v_mfma_f32_16x16x32_bf16 v[20:23], v[132:135], v[242:245], v[20:23]
	v_mfma_f32_16x16x32_bf16 v[52:55], v[140:143], v[242:245], v[52:55]
	s_setprio 0
	s_setprio 1
	v_mfma_f32_16x16x32_bf16 v[16:19], v[144:147], v[160:163], v[16:19]
	v_mfma_f32_16x16x32_bf16 v[44:47], v[152:155], v[160:163], v[44:47]
	v_mfma_f32_16x16x32_bf16 v[12:15], v[144:147], v[168:171], v[12:15]
	v_mfma_f32_16x16x32_bf16 v[36:39], v[152:155], v[168:171], v[36:39]
	v_mfma_f32_16x16x32_bf16 v[4:7], v[144:147], v[198:201], v[4:7]
	v_mfma_f32_16x16x32_bf16 v[28:31], v[152:155], v[198:201], v[28:31]
	v_mfma_f32_16x16x32_bf16 v[0:3], v[144:147], v[238:241], v[0:3]
	v_mfma_f32_16x16x32_bf16 v[8:11], v[152:155], v[238:241], v[8:11]
	v_mfma_f32_16x16x32_bf16 v[16:19], v[148:151], v[164:167], v[16:19]
	v_mfma_f32_16x16x32_bf16 v[44:47], v[156:159], v[164:167], v[44:47]
	v_mfma_f32_16x16x32_bf16 v[12:15], v[148:151], v[172:175], v[12:15]
	v_mfma_f32_16x16x32_bf16 v[36:39], v[156:159], v[172:175], v[36:39]
	v_mfma_f32_16x16x32_bf16 v[4:7], v[148:151], v[202:205], v[4:7]
	v_mfma_f32_16x16x32_bf16 v[28:31], v[156:159], v[202:205], v[28:31]
	v_mfma_f32_16x16x32_bf16 v[0:3], v[148:151], v[242:245], v[0:3]
	v_mfma_f32_16x16x32_bf16 v[8:11], v[156:159], v[242:245], v[8:11]
	s_setprio 0
	s_barrier
	ds_read_b128 v[128:131], v229
	ds_read_b128 v[132:135], v230
	ds_read_b128 v[136:139], v231
	ds_read_b128 v[140:143], v232
	ds_read_b128 v[144:147], v233
	ds_read_b128 v[148:151], v234
	ds_read_b128 v[152:155], v235
	ds_read_b128 v[156:159], v236
	s_mov_b32 m0, s29
	ds_read_b128 v[160:163], v219 offset:32768
	ds_read_b128 v[164:167], v219 offset:33792
	ds_read_b128 v[168:171], v219 offset:34816
	ds_read_b128 v[172:175], v219 offset:35840
	ds_read_b128 v[198:201], v219 offset:36864
	ds_read_b128 v[202:205], v219 offset:37888
	ds_read_b128 v[238:241], v219 offset:38912
	ds_read_b128 v[242:245], v219 offset:39936
	global_load_lds_dwordx4 v192, s[2:3]
	s_mov_b32 m0, s28
	s_nop 0
	global_load_lds_dwordx4 v188, s[2:3]
	s_waitcnt vmcnt(8)
	s_waitcnt lgkmcnt(0)
	s_barrier
	s_setprio 1
	s_waitcnt lgkmcnt(0)
	v_mfma_f32_16x16x32_bf16 v[104:107], v[128:131], v[160:163], v[104:107]
	v_mfma_f32_16x16x32_bf16 v[124:127], v[136:139], v[160:163], v[124:127]
	v_mfma_f32_16x16x32_bf16 v[96:99], v[128:131], v[168:171], v[96:99]
	v_mfma_f32_16x16x32_bf16 v[120:123], v[136:139], v[168:171], v[120:123]
	v_mfma_f32_16x16x32_bf16 v[88:91], v[128:131], v[198:201], v[88:91]
	v_mfma_f32_16x16x32_bf16 v[116:119], v[136:139], v[198:201], v[116:119]
	v_mfma_f32_16x16x32_bf16 v[80:83], v[128:131], v[238:241], v[80:83]
	v_mfma_f32_16x16x32_bf16 v[112:115], v[136:139], v[238:241], v[112:115]
	v_mfma_f32_16x16x32_bf16 v[104:107], v[132:135], v[164:167], v[104:107]
	v_mfma_f32_16x16x32_bf16 v[124:127], v[140:143], v[164:167], v[124:127]
	v_mfma_f32_16x16x32_bf16 v[96:99], v[132:135], v[172:175], v[96:99]
	v_mfma_f32_16x16x32_bf16 v[120:123], v[140:143], v[172:175], v[120:123]
	v_mfma_f32_16x16x32_bf16 v[88:91], v[132:135], v[202:205], v[88:91]
	v_mfma_f32_16x16x32_bf16 v[116:119], v[140:143], v[202:205], v[116:119]
	v_mfma_f32_16x16x32_bf16 v[80:83], v[132:135], v[242:245], v[80:83]
	v_mfma_f32_16x16x32_bf16 v[112:115], v[140:143], v[242:245], v[112:115]
	s_setprio 0
	s_setprio 1
	v_mfma_f32_16x16x32_bf16 v[72:75], v[144:147], v[160:163], v[72:75]
	v_mfma_f32_16x16x32_bf16 v[108:111], v[152:155], v[160:163], v[108:111]
	v_mfma_f32_16x16x32_bf16 v[64:67], v[144:147], v[168:171], v[64:67]
	v_mfma_f32_16x16x32_bf16 v[100:103], v[152:155], v[168:171], v[100:103]
	v_mfma_f32_16x16x32_bf16 v[56:59], v[144:147], v[198:201], v[56:59]
	v_mfma_f32_16x16x32_bf16 v[92:95], v[152:155], v[198:201], v[92:95]
	v_mfma_f32_16x16x32_bf16 v[48:51], v[144:147], v[238:241], v[48:51]
	v_mfma_f32_16x16x32_bf16 v[84:87], v[152:155], v[238:241], v[84:87]
	v_mfma_f32_16x16x32_bf16 v[72:75], v[148:151], v[164:167], v[72:75]
	v_mfma_f32_16x16x32_bf16 v[108:111], v[156:159], v[164:167], v[108:111]
	v_mfma_f32_16x16x32_bf16 v[64:67], v[148:151], v[172:175], v[64:67]
	v_mfma_f32_16x16x32_bf16 v[100:103], v[156:159], v[172:175], v[100:103]
	v_mfma_f32_16x16x32_bf16 v[56:59], v[148:151], v[202:205], v[56:59]
	v_mfma_f32_16x16x32_bf16 v[92:95], v[156:159], v[202:205], v[92:95]
	v_mfma_f32_16x16x32_bf16 v[48:51], v[148:151], v[242:245], v[48:51]
	v_mfma_f32_16x16x32_bf16 v[84:87], v[156:159], v[242:245], v[84:87]
	s_setprio 0
	s_barrier
	s_mov_b32 m0, s31
	v_lshl_add_u64 v[214:215], v[246:247], 0, s[0:1]
	ds_read_b128 v[160:163], v219 offset:49152
	ds_read_b128 v[164:167], v219 offset:50176
	ds_read_b128 v[168:171], v219 offset:51200
	ds_read_b128 v[172:175], v219 offset:52224
	ds_read_b128 v[198:201], v219 offset:53248
	ds_read_b128 v[202:205], v219 offset:54272
	ds_read_b128 v[238:241], v219 offset:55296
	ds_read_b128 v[242:245], v219 offset:56320
	global_load_lds_dwordx4 v[214:215], off
	v_lshl_add_u64 v[214:215], v[248:249], 0, s[0:1]
	s_mov_b32 m0, s30
	s_nop 0
	global_load_lds_dwordx4 v[214:215], off
	s_mov_b32 m0, s95
	s_nop 0
	global_load_lds_dwordx4 v190, s[84:85]
	s_mov_b32 m0, s94
	s_nop 0
	global_load_lds_dwordx4 v186, s[84:85]
	v_lshl_add_u64 v[214:215], v[250:251], 0, s[0:1]
	s_mov_b32 m0, s35
	s_nop 0
	global_load_lds_dwordx4 v[214:215], off
	v_lshl_add_u64 v[214:215], v[252:253], 0, s[0:1]
	s_mov_b32 m0, s34
	s_nop 0
	global_load_lds_dwordx4 v[214:215], off
	s_waitcnt vmcnt(8)
	s_waitcnt lgkmcnt(0)
	s_barrier
	s_setprio 1
	s_waitcnt lgkmcnt(0)
	v_mfma_f32_16x16x32_bf16 v[40:43], v[128:131], v[160:163], v[40:43]
	v_mfma_f32_16x16x32_bf16 v[76:79], v[136:139], v[160:163], v[76:79]
	v_mfma_f32_16x16x32_bf16 v[32:35], v[128:131], v[168:171], v[32:35]
	v_mfma_f32_16x16x32_bf16 v[68:71], v[136:139], v[168:171], v[68:71]
	v_mfma_f32_16x16x32_bf16 v[24:27], v[128:131], v[198:201], v[24:27]
	v_mfma_f32_16x16x32_bf16 v[60:63], v[136:139], v[198:201], v[60:63]
	v_mfma_f32_16x16x32_bf16 v[20:23], v[128:131], v[238:241], v[20:23]
	v_mfma_f32_16x16x32_bf16 v[52:55], v[136:139], v[238:241], v[52:55]
	v_mfma_f32_16x16x32_bf16 v[40:43], v[132:135], v[164:167], v[40:43]
	v_mfma_f32_16x16x32_bf16 v[76:79], v[140:143], v[164:167], v[76:79]
	v_mfma_f32_16x16x32_bf16 v[32:35], v[132:135], v[172:175], v[32:35]
	v_mfma_f32_16x16x32_bf16 v[68:71], v[140:143], v[172:175], v[68:71]
	v_mfma_f32_16x16x32_bf16 v[24:27], v[132:135], v[202:205], v[24:27]
	v_mfma_f32_16x16x32_bf16 v[60:63], v[140:143], v[202:205], v[60:63]
	v_mfma_f32_16x16x32_bf16 v[20:23], v[132:135], v[242:245], v[20:23]
	v_mfma_f32_16x16x32_bf16 v[52:55], v[140:143], v[242:245], v[52:55]
	s_setprio 0
	s_setprio 1
	v_mfma_f32_16x16x32_bf16 v[16:19], v[144:147], v[160:163], v[16:19]
	v_mfma_f32_16x16x32_bf16 v[44:47], v[152:155], v[160:163], v[44:47]
	v_mfma_f32_16x16x32_bf16 v[12:15], v[144:147], v[168:171], v[12:15]
	v_mfma_f32_16x16x32_bf16 v[36:39], v[152:155], v[168:171], v[36:39]
	v_mfma_f32_16x16x32_bf16 v[4:7], v[144:147], v[198:201], v[4:7]
	v_mfma_f32_16x16x32_bf16 v[28:31], v[152:155], v[198:201], v[28:31]
	v_mfma_f32_16x16x32_bf16 v[0:3], v[144:147], v[238:241], v[0:3]
	v_mfma_f32_16x16x32_bf16 v[8:11], v[152:155], v[238:241], v[8:11]
	v_mfma_f32_16x16x32_bf16 v[16:19], v[148:151], v[164:167], v[16:19]
	v_mfma_f32_16x16x32_bf16 v[44:47], v[156:159], v[164:167], v[44:47]
	v_mfma_f32_16x16x32_bf16 v[12:15], v[148:151], v[172:175], v[12:15]
	v_mfma_f32_16x16x32_bf16 v[36:39], v[156:159], v[172:175], v[36:39]
	v_mfma_f32_16x16x32_bf16 v[4:7], v[148:151], v[202:205], v[4:7]
	v_mfma_f32_16x16x32_bf16 v[28:31], v[156:159], v[202:205], v[28:31]
	v_mfma_f32_16x16x32_bf16 v[0:3], v[148:151], v[242:245], v[0:3]
	v_mfma_f32_16x16x32_bf16 v[8:11], v[156:159], v[242:245], v[8:11]
	s_setprio 0
	s_barrier
	s_movk_i32 s2, 0x100
	s_andn2_b64 vcc, exec, s[38:39]
	s_mov_b64 s[84:85], -1
	s_mov_b64 s[38:39], 0
	s_cbranch_vccz .LBB0_42
	s_and_b64 vcc, exec, s[40:41]
	s_cbranch_vccz .LBB0_45
	s_barrier

.LBB0_157:
	v_or_b32_e32 v138, 0x10000, v142
	v_add_u32_e32 v139, 0x10400, v142
	ds_read_b128 v[144:147], v138
	ds_read_b128 v[148:151], v139
	v_add_u32_e32 v138, 0x10800, v142
	v_add_u32_e32 v139, 0x10c00, v142
	ds_read_b128 v[152:155], v138
	ds_read_b128 v[156:159], v139
	v_or_b32_e32 v138, 0x14000, v142
	v_add_u32_e32 v139, 0x14400, v142
	ds_read_b128 v[160:163], v138
	ds_read_b128 v[164:167], v139
	v_add_u32_e32 v138, 0x14800, v142
	v_add_u32_e32 v139, 0x14c00, v142
	ds_read_b128 v[168:171], v138
	ds_read_b128 v[172:175], v139
	s_add_u32 s8, vcc_lo, 0xfffc0080
	s_addc_u32 s9, vcc_hi, -1
	s_cmp_eq_u32 s90, 12
	s_cselect_b32 s11, s5, s9
	s_cselect_b32 s10, s92, s8
	s_cselect_b32 s9, s85, s89
	s_cselect_b32 s8, s96, s88
	v_lshl_add_u64 v[138:139], vcc, 0, v[134:135]
	s_add_i32 m0, s23, 0xc000
	ds_read_b128 v[186:189], v141
	ds_read_b128 v[190:193], v141 offset:1024
	ds_read_b128 v[194:197], v141 offset:2048
	ds_read_b128 v[198:201], v141 offset:3072
	ds_read_b128 v[202:205], v141 offset:4096
	ds_read_b128 v[220:223], v141 offset:5120
	ds_read_b128 v[224:227], v141 offset:6144
	ds_read_b128 v[228:231], v141 offset:7168
	global_load_lds_dwordx4 v[138:139], off
	v_lshl_add_u64 v[138:139], vcc, 0, v[136:137]
	s_add_i32 m0, s23, 0xe000
	s_nop 0
	global_load_lds_dwordx4 v[138:139], off
	s_waitcnt vmcnt(8)
	s_waitcnt lgkmcnt(0)
	s_barrier
	s_setprio 1
	s_waitcnt lgkmcnt(0)
	v_mfma_f32_16x16x32_bf16 v[124:127], v[144:147], v[186:189], v[124:127]
	v_mfma_f32_16x16x32_bf16 v[120:123], v[152:155], v[186:189], v[120:123]
	v_mfma_f32_16x16x32_bf16 v[108:111], v[144:147], v[194:197], v[108:111]
	v_mfma_f32_16x16x32_bf16 v[104:107], v[152:155], v[194:197], v[104:107]
	v_mfma_f32_16x16x32_bf16 v[92:95], v[144:147], v[202:205], v[92:95]
	v_mfma_f32_16x16x32_bf16 v[88:91], v[152:155], v[202:205], v[88:91]
	v_mfma_f32_16x16x32_bf16 v[76:79], v[144:147], v[224:227], v[76:79]
	v_mfma_f32_16x16x32_bf16 v[72:75], v[152:155], v[224:227], v[72:75]
	v_mfma_f32_16x16x32_bf16 v[124:127], v[148:151], v[190:193], v[124:127]
	v_mfma_f32_16x16x32_bf16 v[120:123], v[156:159], v[190:193], v[120:123]
	v_mfma_f32_16x16x32_bf16 v[108:111], v[148:151], v[198:201], v[108:111]
	v_mfma_f32_16x16x32_bf16 v[104:107], v[156:159], v[198:201], v[104:107]
	v_mfma_f32_16x16x32_bf16 v[92:95], v[148:151], v[220:223], v[92:95]
	v_mfma_f32_16x16x32_bf16 v[88:91], v[156:159], v[220:223], v[88:91]
	v_mfma_f32_16x16x32_bf16 v[76:79], v[148:151], v[228:231], v[76:79]
	v_mfma_f32_16x16x32_bf16 v[72:75], v[156:159], v[228:231], v[72:75]
	s_setprio 0
	s_setprio 1
	v_mfma_f32_16x16x32_bf16 v[116:119], v[160:163], v[186:189], v[116:119]
	v_mfma_f32_16x16x32_bf16 v[112:115], v[168:171], v[186:189], v[112:115]
	v_mfma_f32_16x16x32_bf16 v[100:103], v[160:163], v[194:197], v[100:103]
	v_mfma_f32_16x16x32_bf16 v[96:99], v[168:171], v[194:197], v[96:99]
	v_mfma_f32_16x16x32_bf16 v[84:87], v[160:163], v[202:205], v[84:87]
	v_mfma_f32_16x16x32_bf16 v[80:83], v[168:171], v[202:205], v[80:83]
	v_mfma_f32_16x16x32_bf16 v[68:71], v[160:163], v[224:227], v[68:71]
	v_mfma_f32_16x16x32_bf16 v[64:67], v[168:171], v[224:227], v[64:67]
	v_mfma_f32_16x16x32_bf16 v[116:119], v[164:167], v[190:193], v[116:119]
	v_mfma_f32_16x16x32_bf16 v[112:115], v[172:175], v[190:193], v[112:115]
	v_mfma_f32_16x16x32_bf16 v[100:103], v[164:167], v[198:201], v[100:103]
	v_mfma_f32_16x16x32_bf16 v[96:99], v[172:175], v[198:201], v[96:99]
	v_mfma_f32_16x16x32_bf16 v[84:87], v[164:167], v[220:223], v[84:87]
	v_mfma_f32_16x16x32_bf16 v[80:83], v[172:175], v[220:223], v[80:83]
	v_mfma_f32_16x16x32_bf16 v[68:71], v[164:167], v[228:231], v[68:71]
	v_mfma_f32_16x16x32_bf16 v[64:67], v[172:175], v[228:231], v[64:67]
	s_setprio 0
	s_barrier
	s_mov_b32 m0, s25
	v_lshl_add_u64 v[138:139], s[8:9], 0, v[176:177]
	s_add_u32 s60, s8, 0x40000
	ds_read_b128 v[186:189], v141 offset:16384
	ds_read_b128 v[190:193], v141 offset:17408
	ds_read_b128 v[194:197], v141 offset:18432
	ds_read_b128 v[198:201], v141 offset:19456
	ds_read_b128 v[202:205], v141 offset:20480
	ds_read_b128 v[220:223], v141 offset:21504
	ds_read_b128 v[224:227], v141 offset:22528
	ds_read_b128 v[228:231], v141 offset:23552
	global_load_lds_dwordx4 v[138:139], off
	v_lshl_add_u64 v[232:233], s[8:9], 0, v[128:129]
	s_mov_b32 m0, s26
	s_addc_u32 s61, s9, 0
	global_load_lds_dwordx4 v[232:233], off
	s_mov_b32 m0, s27
	v_lshl_add_u64 v[236:237], s[10:11], 0, v[130:131]
	global_load_lds_dwordx4 v176, s[60:61]
	s_mov_b32 m0, s28
	s_nop 0
	global_load_lds_dwordx4 v128, s[60:61]
	v_lshl_add_u64 v[234:235], s[10:11], 0, v[132:133]
	s_mov_b32 m0, s23
	s_nop 0
	global_load_lds_dwordx4 v[234:235], off
	s_mov_b32 m0, s29
	s_nop 0
	global_load_lds_dwordx4 v[236:237], off
	s_waitcnt vmcnt(8)
	s_waitcnt lgkmcnt(0)
	s_barrier
	s_setprio 1
	s_waitcnt lgkmcnt(0)
	v_mfma_f32_16x16x32_bf16 v[60:63], v[144:147], v[186:189], v[60:63]
	v_mfma_f32_16x16x32_bf16 v[56:59], v[152:155], v[186:189], v[56:59]
	v_mfma_f32_16x16x32_bf16 v[44:47], v[144:147], v[194:197], v[44:47]
	v_mfma_f32_16x16x32_bf16 v[40:43], v[152:155], v[194:197], v[40:43]
	v_mfma_f32_16x16x32_bf16 v[28:31], v[144:147], v[202:205], v[28:31]
	v_mfma_f32_16x16x32_bf16 v[24:27], v[152:155], v[202:205], v[24:27]
	v_mfma_f32_16x16x32_bf16 v[12:15], v[144:147], v[224:227], v[12:15]
	v_mfma_f32_16x16x32_bf16 v[8:11], v[152:155], v[224:227], v[8:11]
	v_mfma_f32_16x16x32_bf16 v[60:63], v[148:151], v[190:193], v[60:63]
	v_mfma_f32_16x16x32_bf16 v[56:59], v[156:159], v[190:193], v[56:59]
	v_mfma_f32_16x16x32_bf16 v[44:47], v[148:151], v[198:201], v[44:47]
	v_mfma_f32_16x16x32_bf16 v[40:43], v[156:159], v[198:201], v[40:43]
	v_mfma_f32_16x16x32_bf16 v[28:31], v[148:151], v[220:223], v[28:31]
	v_mfma_f32_16x16x32_bf16 v[24:27], v[156:159], v[220:223], v[24:27]
	v_mfma_f32_16x16x32_bf16 v[12:15], v[148:151], v[228:231], v[12:15]
	v_mfma_f32_16x16x32_bf16 v[8:11], v[156:159], v[228:231], v[8:11]
	s_setprio 0
	s_setprio 1
	v_mfma_f32_16x16x32_bf16 v[52:55], v[160:163], v[186:189], v[52:55]
	v_mfma_f32_16x16x32_bf16 v[48:51], v[168:171], v[186:189], v[48:51]
	v_mfma_f32_16x16x32_bf16 v[36:39], v[160:163], v[194:197], v[36:39]
	v_mfma_f32_16x16x32_bf16 v[32:35], v[168:171], v[194:197], v[32:35]
	v_mfma_f32_16x16x32_bf16 v[20:23], v[160:163], v[202:205], v[20:23]
	v_mfma_f32_16x16x32_bf16 v[16:19], v[168:171], v[202:205], v[16:19]
	v_mfma_f32_16x16x32_bf16 v[4:7], v[160:163], v[224:227], v[4:7]
	v_mfma_f32_16x16x32_bf16 v[0:3], v[168:171], v[224:227], v[0:3]
	v_mfma_f32_16x16x32_bf16 v[52:55], v[164:167], v[190:193], v[52:55]
	v_mfma_f32_16x16x32_bf16 v[48:51], v[172:175], v[190:193], v[48:51]
	v_mfma_f32_16x16x32_bf16 v[36:39], v[164:167], v[198:201], v[36:39]
	v_mfma_f32_16x16x32_bf16 v[32:35], v[172:175], v[198:201], v[32:35]
	v_mfma_f32_16x16x32_bf16 v[20:23], v[164:167], v[220:223], v[20:23]
	v_mfma_f32_16x16x32_bf16 v[16:19], v[172:175], v[220:223], v[16:19]
	v_mfma_f32_16x16x32_bf16 v[4:7], v[164:167], v[228:231], v[4:7]
	v_mfma_f32_16x16x32_bf16 v[0:3], v[172:175], v[228:231], v[0:3]
	s_setprio 0
	s_barrier
	v_or_b32_e32 v144, 0x18000, v142
	v_add_u32_e32 v148, 0x18400, v142
	v_add_u32_e32 v152, 0x18800, v142
	v_add_u32_e32 v156, 0x18c00, v142
	v_or_b32_e32 v160, 0x1c000, v142
	v_add_u32_e32 v164, 0x1c400, v142
	v_add_u32_e32 v168, 0x1c800, v142
	v_add_u32_e32 v172, 0x1cc00, v142
	ds_read_b128 v[144:147], v144
	ds_read_b128 v[148:151], v148
	ds_read_b128 v[152:155], v152
	ds_read_b128 v[156:159], v156
	ds_read_b128 v[160:163], v160
	ds_read_b128 v[164:167], v164
	ds_read_b128 v[168:171], v168
	ds_read_b128 v[172:175], v172
	s_add_u32 s10, s10, 0x40000
	s_addc_u32 s11, s11, 0
	s_mov_b32 m0, s30
	ds_read_b128 v[186:189], v141 offset:32768
	ds_read_b128 v[190:193], v141 offset:33792
	ds_read_b128 v[194:197], v141 offset:34816
	ds_read_b128 v[198:201], v141 offset:35840
	ds_read_b128 v[202:205], v141 offset:36864
	ds_read_b128 v[220:223], v141 offset:37888
	ds_read_b128 v[224:227], v141 offset:38912
	ds_read_b128 v[228:231], v141 offset:39936
	global_load_lds_dwordx4 v132, s[10:11]
	v_lshl_add_u64 v[238:239], s[10:11], 0, v[130:131]
	s_mov_b32 m0, s31
	s_nop 0
	global_load_lds_dwordx4 v[238:239], off
	s_waitcnt vmcnt(8)
	s_waitcnt lgkmcnt(0)
	s_barrier
	s_setprio 1
	s_waitcnt lgkmcnt(0)
	v_mfma_f32_16x16x32_bf16 v[124:127], v[144:147], v[186:189], v[124:127]
	v_mfma_f32_16x16x32_bf16 v[120:123], v[152:155], v[186:189], v[120:123]
	v_mfma_f32_16x16x32_bf16 v[108:111], v[144:147], v[194:197], v[108:111]
	v_mfma_f32_16x16x32_bf16 v[104:107], v[152:155], v[194:197], v[104:107]
	v_mfma_f32_16x16x32_bf16 v[92:95], v[144:147], v[202:205], v[92:95]
	v_mfma_f32_16x16x32_bf16 v[88:91], v[152:155], v[202:205], v[88:91]
	v_mfma_f32_16x16x32_bf16 v[76:79], v[144:147], v[224:227], v[76:79]
	v_mfma_f32_16x16x32_bf16 v[72:75], v[152:155], v[224:227], v[72:75]
	v_mfma_f32_16x16x32_bf16 v[124:127], v[148:151], v[190:193], v[124:127]
	v_mfma_f32_16x16x32_bf16 v[120:123], v[156:159], v[190:193], v[120:123]
	v_mfma_f32_16x16x32_bf16 v[108:111], v[148:151], v[198:201], v[108:111]
	v_mfma_f32_16x16x32_bf16 v[104:107], v[156:159], v[198:201], v[104:107]
	v_mfma_f32_16x16x32_bf16 v[92:95], v[148:151], v[220:223], v[92:95]
	v_mfma_f32_16x16x32_bf16 v[88:91], v[156:159], v[220:223], v[88:91]
	v_mfma_f32_16x16x32_bf16 v[76:79], v[148:151], v[228:231], v[76:79]
	v_mfma_f32_16x16x32_bf16 v[72:75], v[156:159], v[228:231], v[72:75]
	s_setprio 0
	s_setprio 1
	v_mfma_f32_16x16x32_bf16 v[116:119], v[160:163], v[186:189], v[116:119]
	v_mfma_f32_16x16x32_bf16 v[112:115], v[168:171], v[186:189], v[112:115]
	v_mfma_f32_16x16x32_bf16 v[100:103], v[160:163], v[194:197], v[100:103]
	v_mfma_f32_16x16x32_bf16 v[96:99], v[168:171], v[194:197], v[96:99]
	v_mfma_f32_16x16x32_bf16 v[84:87], v[160:163], v[202:205], v[84:87]
	v_mfma_f32_16x16x32_bf16 v[80:83], v[168:171], v[202:205], v[80:83]
	v_mfma_f32_16x16x32_bf16 v[68:71], v[160:163], v[224:227], v[68:71]
	v_mfma_f32_16x16x32_bf16 v[64:67], v[168:171], v[224:227], v[64:67]
	v_mfma_f32_16x16x32_bf16 v[116:119], v[164:167], v[190:193], v[116:119]
	v_mfma_f32_16x16x32_bf16 v[112:115], v[172:175], v[190:193], v[112:115]
	v_mfma_f32_16x16x32_bf16 v[100:103], v[164:167], v[198:201], v[100:103]
	v_mfma_f32_16x16x32_bf16 v[96:99], v[172:175], v[198:201], v[96:99]
	v_mfma_f32_16x16x32_bf16 v[84:87], v[164:167], v[220:223], v[84:87]
	v_mfma_f32_16x16x32_bf16 v[80:83], v[172:175], v[220:223], v[80:83]
	v_mfma_f32_16x16x32_bf16 v[68:71], v[164:167], v[228:231], v[68:71]
	v_mfma_f32_16x16x32_bf16 v[64:67], v[172:175], v[228:231], v[64:67]
	s_setprio 0
	s_barrier
	s_mov_b32 m0, s34
	v_lshl_add_u64 v[138:139], v[138:139], 0, s[0:1]
	s_add_u32 s8, s8, 0x40080
	ds_read_b128 v[186:189], v141 offset:49152
	ds_read_b128 v[190:193], v141 offset:50176
	ds_read_b128 v[194:197], v141 offset:51200
	ds_read_b128 v[198:201], v141 offset:52224
	ds_read_b128 v[202:205], v141 offset:53248
	ds_read_b128 v[220:223], v141 offset:54272
	ds_read_b128 v[224:227], v141 offset:55296
	ds_read_b128 v[228:231], v141 offset:56320
	global_load_lds_dwordx4 v[138:139], off
	v_lshl_add_u64 v[138:139], v[232:233], 0, s[0:1]
	s_mov_b32 m0, s35
	s_addc_u32 s9, s9, 0
	global_load_lds_dwordx4 v[138:139], off
	s_mov_b32 m0, s74
	s_nop 0
	global_load_lds_dwordx4 v176, s[8:9]
	s_mov_b32 m0, s75
	s_nop 0
	global_load_lds_dwordx4 v128, s[8:9]
	v_lshl_add_u64 v[138:139], v[234:235], 0, s[0:1]
	s_mov_b32 m0, s42
	s_nop 0
	global_load_lds_dwordx4 v[138:139], off
	v_lshl_add_u64 v[138:139], v[236:237], 0, s[0:1]
	s_mov_b32 m0, s43
	s_nop 0
	global_load_lds_dwordx4 v[138:139], off
	s_waitcnt vmcnt(8)
	s_waitcnt lgkmcnt(0)
	s_barrier
	s_setprio 1
	s_waitcnt lgkmcnt(0)
	v_mfma_f32_16x16x32_bf16 v[60:63], v[144:147], v[186:189], v[60:63]
	v_mfma_f32_16x16x32_bf16 v[56:59], v[152:155], v[186:189], v[56:59]
	v_mfma_f32_16x16x32_bf16 v[44:47], v[144:147], v[194:197], v[44:47]
	v_mfma_f32_16x16x32_bf16 v[40:43], v[152:155], v[194:197], v[40:43]
	v_mfma_f32_16x16x32_bf16 v[28:31], v[144:147], v[202:205], v[28:31]
	v_mfma_f32_16x16x32_bf16 v[24:27], v[152:155], v[202:205], v[24:27]
	v_mfma_f32_16x16x32_bf16 v[12:15], v[144:147], v[224:227], v[12:15]
	v_mfma_f32_16x16x32_bf16 v[8:11], v[152:155], v[224:227], v[8:11]
	v_mfma_f32_16x16x32_bf16 v[60:63], v[148:151], v[190:193], v[60:63]
	v_mfma_f32_16x16x32_bf16 v[56:59], v[156:159], v[190:193], v[56:59]
	v_mfma_f32_16x16x32_bf16 v[44:47], v[148:151], v[198:201], v[44:47]
	v_mfma_f32_16x16x32_bf16 v[40:43], v[156:159], v[198:201], v[40:43]
	v_mfma_f32_16x16x32_bf16 v[28:31], v[148:151], v[220:223], v[28:31]
	v_mfma_f32_16x16x32_bf16 v[24:27], v[156:159], v[220:223], v[24:27]
	v_mfma_f32_16x16x32_bf16 v[12:15], v[148:151], v[228:231], v[12:15]
	v_mfma_f32_16x16x32_bf16 v[8:11], v[156:159], v[228:231], v[8:11]
	s_setprio 0
	s_setprio 1
	v_mfma_f32_16x16x32_bf16 v[52:55], v[160:163], v[186:189], v[52:55]
	v_mfma_f32_16x16x32_bf16 v[48:51], v[168:171], v[186:189], v[48:51]
	v_mfma_f32_16x16x32_bf16 v[36:39], v[160:163], v[194:197], v[36:39]
	v_mfma_f32_16x16x32_bf16 v[32:35], v[168:171], v[194:197], v[32:35]
	v_mfma_f32_16x16x32_bf16 v[20:23], v[160:163], v[202:205], v[20:23]
	v_mfma_f32_16x16x32_bf16 v[16:19], v[168:171], v[202:205], v[16:19]
	v_mfma_f32_16x16x32_bf16 v[4:7], v[160:163], v[224:227], v[4:7]
	v_mfma_f32_16x16x32_bf16 v[0:3], v[168:171], v[224:227], v[0:3]
	v_mfma_f32_16x16x32_bf16 v[52:55], v[164:167], v[190:193], v[52:55]
	v_mfma_f32_16x16x32_bf16 v[48:51], v[172:175], v[190:193], v[48:51]
	v_mfma_f32_16x16x32_bf16 v[36:39], v[164:167], v[198:201], v[36:39]
	v_mfma_f32_16x16x32_bf16 v[32:35], v[172:175], v[198:201], v[32:35]
	v_mfma_f32_16x16x32_bf16 v[20:23], v[164:167], v[220:223], v[20:23]
	v_mfma_f32_16x16x32_bf16 v[16:19], v[172:175], v[220:223], v[16:19]
	v_mfma_f32_16x16x32_bf16 v[4:7], v[164:167], v[228:231], v[4:7]
	v_mfma_f32_16x16x32_bf16 v[0:3], v[172:175], v[228:231], v[0:3]
	s_setprio 0
	s_barrier
	s_add_i32 s90, s90, 2
	s_add_u32 vcc_lo, vcc_lo, 0x100
	s_addc_u32 vcc_hi, vcc_hi, 0
	s_add_u32 s88, s88, 0x100
	s_addc_u32 s89, s89, 0
	s_cmp_gt_u32 s90, 13
	s_cbranch_scc0 .LBB0_157
	s_and_b64 vcc, exec, s[40:41]
	s_cbranch_vccz .LBB0_160
	s_barrier

.LBB0_326:
	v_or_b32_e32 v13, 0x10000, v12
	v_add_u32_e32 v18, 0x10400, v12
	ds_read_b128 v[14:17], v13
	ds_read_b128 v[18:21], v18
	v_add_u32_e32 v13, 0x10800, v12
	v_add_u32_e32 v26, 0x10c00, v12
	s_add_u32 s2, s40, s90
	ds_read_b128 v[22:25], v13
	ds_read_b128 v[26:29], v26
	v_or_b32_e32 v13, 0x14000, v12
	s_addc_u32 s3, s41, s91
	v_add_u32_e32 v30, 0x14400, v12
	ds_read_b128 v[160:163], v13
	ds_read_b128 v[164:167], v30
	v_add_u32_e32 v13, 0x14800, v12
	s_add_u32 s2, s2, 0x100
	v_add_u32_e32 v30, 0x14c00, v12
	ds_read_b128 v[168:171], v13
	ds_read_b128 v[172:175], v30
	s_addc_u32 s3, s3, 0
	s_add_u32 s60, s75, s90
	s_addc_u32 s61, s83, s91
	s_cmpk_eq_i32 s90, 0x700
	s_cselect_b32 s7, s85, s3
	s_cselect_b32 s6, s92, s2
	s_cselect_b32 s3, s5, s61
	s_cselect_b32 s2, s94, s60
	v_lshl_add_u64 v[30:31], v[6:7], 0, s[90:91]
	s_add_i32 m0, s22, 0xc000
	ds_read_b128 v[186:189], v11
	ds_read_b128 v[194:197], v11 offset:1024
	ds_read_b128 v[198:201], v11 offset:2048
	ds_read_b128 v[202:205], v11 offset:3072
	ds_read_b128 v[220:223], v11 offset:4096
	ds_read_b128 v[224:227], v11 offset:5120
	ds_read_b128 v[228:231], v11 offset:6144
	ds_read_b128 v[232:235], v11 offset:7168
	global_load_lds_dwordx4 v[30:31], off
	v_lshl_add_u64 v[30:31], v[8:9], 0, s[90:91]
	s_add_i32 m0, s22, 0xe000
	s_nop 0
	global_load_lds_dwordx4 v[30:31], off
	s_waitcnt vmcnt(8)
	s_waitcnt lgkmcnt(0)
	s_barrier
	s_setprio 1
	s_waitcnt lgkmcnt(0)
	v_mfma_f32_16x16x32_bf16 v[156:159], v[14:17], v[186:189], v[156:159]
	v_mfma_f32_16x16x32_bf16 v[152:155], v[22:25], v[186:189], v[152:155]
	v_mfma_f32_16x16x32_bf16 v[140:143], v[14:17], v[198:201], v[140:143]
	v_mfma_f32_16x16x32_bf16 v[136:139], v[22:25], v[198:201], v[136:139]
	v_mfma_f32_16x16x32_bf16 v[124:127], v[14:17], v[220:223], v[124:127]
	v_mfma_f32_16x16x32_bf16 v[120:123], v[22:25], v[220:223], v[120:123]
	v_mfma_f32_16x16x32_bf16 v[108:111], v[14:17], v[228:231], v[108:111]
	v_mfma_f32_16x16x32_bf16 v[104:107], v[22:25], v[228:231], v[104:107]
	v_mfma_f32_16x16x32_bf16 v[156:159], v[18:21], v[194:197], v[156:159]
	v_mfma_f32_16x16x32_bf16 v[152:155], v[26:29], v[194:197], v[152:155]
	v_mfma_f32_16x16x32_bf16 v[140:143], v[18:21], v[202:205], v[140:143]
	v_mfma_f32_16x16x32_bf16 v[136:139], v[26:29], v[202:205], v[136:139]
	v_mfma_f32_16x16x32_bf16 v[124:127], v[18:21], v[224:227], v[124:127]
	v_mfma_f32_16x16x32_bf16 v[120:123], v[26:29], v[224:227], v[120:123]
	v_mfma_f32_16x16x32_bf16 v[108:111], v[18:21], v[232:235], v[108:111]
	v_mfma_f32_16x16x32_bf16 v[104:107], v[26:29], v[232:235], v[104:107]
	s_setprio 0
	s_setprio 1
	v_mfma_f32_16x16x32_bf16 v[148:151], v[160:163], v[186:189], v[148:151]
	v_mfma_f32_16x16x32_bf16 v[144:147], v[168:171], v[186:189], v[144:147]
	v_mfma_f32_16x16x32_bf16 v[132:135], v[160:163], v[198:201], v[132:135]
	v_mfma_f32_16x16x32_bf16 v[128:131], v[168:171], v[198:201], v[128:131]
	v_mfma_f32_16x16x32_bf16 v[116:119], v[160:163], v[220:223], v[116:119]
	v_mfma_f32_16x16x32_bf16 v[112:115], v[168:171], v[220:223], v[112:115]
	v_mfma_f32_16x16x32_bf16 v[100:103], v[160:163], v[228:231], v[100:103]
	v_mfma_f32_16x16x32_bf16 v[96:99], v[168:171], v[228:231], v[96:99]
	v_mfma_f32_16x16x32_bf16 v[148:151], v[164:167], v[194:197], v[148:151]
	v_mfma_f32_16x16x32_bf16 v[144:147], v[172:175], v[194:197], v[144:147]
	v_mfma_f32_16x16x32_bf16 v[132:135], v[164:167], v[202:205], v[132:135]
	v_mfma_f32_16x16x32_bf16 v[128:131], v[172:175], v[202:205], v[128:131]
	v_mfma_f32_16x16x32_bf16 v[116:119], v[164:167], v[224:227], v[116:119]
	v_mfma_f32_16x16x32_bf16 v[112:115], v[172:175], v[224:227], v[112:115]
	v_mfma_f32_16x16x32_bf16 v[100:103], v[164:167], v[232:235], v[100:103]
	v_mfma_f32_16x16x32_bf16 v[96:99], v[172:175], v[232:235], v[96:99]
	s_setprio 0
	s_barrier
	s_mov_b32 m0, s23
	v_lshl_add_u64 v[190:191], s[2:3], 0, v[176:177]
	s_add_u32 s60, s2, 0x40000
	ds_read_b128 v[186:189], v11 offset:16384
	ds_read_b128 v[194:197], v11 offset:17408
	ds_read_b128 v[198:201], v11 offset:18432
	ds_read_b128 v[202:205], v11 offset:19456
	ds_read_b128 v[220:223], v11 offset:20480
	ds_read_b128 v[224:227], v11 offset:21504
	ds_read_b128 v[228:231], v11 offset:22528
	ds_read_b128 v[232:235], v11 offset:23552
	global_load_lds_dwordx4 v[190:191], off
	v_lshl_add_u64 v[214:215], s[2:3], 0, v[0:1]
	s_mov_b32 m0, s24
	s_addc_u32 s61, s3, 0
	global_load_lds_dwordx4 v[214:215], off
	s_mov_b32 m0, s25
	v_lshl_add_u64 v[236:237], s[6:7], 0, v[176:177]
	global_load_lds_dwordx4 v176, s[60:61]
	s_mov_b32 m0, s26
	v_lshl_add_u64 v[238:239], s[6:7], 0, v[0:1]
	global_load_lds_dwordx4 v0, s[60:61]
	s_mov_b32 m0, s22
	s_nop 0
	global_load_lds_dwordx4 v[236:237], off
	s_mov_b32 m0, s27
	s_nop 0
	global_load_lds_dwordx4 v[238:239], off
	s_waitcnt vmcnt(8)
	s_waitcnt lgkmcnt(0)
	s_barrier
	s_setprio 1
	s_waitcnt lgkmcnt(0)
	v_mfma_f32_16x16x32_bf16 v[92:95], v[14:17], v[186:189], v[92:95]
	v_mfma_f32_16x16x32_bf16 v[88:91], v[22:25], v[186:189], v[88:91]
	v_mfma_f32_16x16x32_bf16 v[76:79], v[14:17], v[198:201], v[76:79]
	v_mfma_f32_16x16x32_bf16 v[72:75], v[22:25], v[198:201], v[72:75]
	v_mfma_f32_16x16x32_bf16 v[60:63], v[14:17], v[220:223], v[60:63]
	v_mfma_f32_16x16x32_bf16 v[56:59], v[22:25], v[220:223], v[56:59]
	v_mfma_f32_16x16x32_bf16 v[14:17], v[14:17], v[228:231], v[44:47]
	v_mfma_f32_16x16x32_bf16 v[92:95], v[18:21], v[194:197], v[92:95]
	v_mfma_f32_16x16x32_bf16 v[88:91], v[26:29], v[194:197], v[88:91]
	v_mfma_f32_16x16x32_bf16 v[76:79], v[18:21], v[202:205], v[76:79]
	v_mfma_f32_16x16x32_bf16 v[72:75], v[26:29], v[202:205], v[72:75]
	v_mfma_f32_16x16x32_bf16 v[60:63], v[18:21], v[224:227], v[60:63]
	v_mfma_f32_16x16x32_bf16 v[56:59], v[26:29], v[224:227], v[56:59]
	v_mfma_f32_16x16x32_bf16 v[14:17], v[18:21], v[232:235], v[14:17]
	v_mfma_f32_16x16x32_bf16 v[18:21], v[22:25], v[228:231], v[40:43]
	v_mfma_f32_16x16x32_bf16 v[18:21], v[26:29], v[232:235], v[18:21]
	s_setprio 0
	s_setprio 1
	v_mfma_f32_16x16x32_bf16 v[40:43], v[160:163], v[198:201], v[68:71]
	v_mfma_f32_16x16x32_bf16 v[68:71], v[164:167], v[202:205], v[40:43]
	v_mfma_f32_16x16x32_bf16 v[40:43], v[168:171], v[198:201], v[64:67]
	v_mfma_f32_16x16x32_bf16 v[64:67], v[172:175], v[202:205], v[40:43]
	v_mfma_f32_16x16x32_bf16 v[40:43], v[160:163], v[220:223], v[52:55]
	v_mfma_f32_16x16x32_bf16 v[52:55], v[164:167], v[224:227], v[40:43]
	v_mfma_f32_16x16x32_bf16 v[40:43], v[168:171], v[220:223], v[48:51]
	v_mfma_f32_16x16x32_bf16 v[36:39], v[160:163], v[228:231], v[36:39]
	v_mfma_f32_16x16x32_bf16 v[30:33], v[168:171], v[228:231], v[32:35]
	v_mfma_f32_16x16x32_bf16 v[22:25], v[160:163], v[186:189], v[84:87]
	v_mfma_f32_16x16x32_bf16 v[26:29], v[168:171], v[186:189], v[80:83]
	v_mfma_f32_16x16x32_bf16 v[48:51], v[172:175], v[224:227], v[40:43]
	v_mfma_f32_16x16x32_bf16 v[36:39], v[164:167], v[232:235], v[36:39]
	v_mfma_f32_16x16x32_bf16 v[30:33], v[172:175], v[232:235], v[30:33]
	v_mfma_f32_16x16x32_bf16 v[22:25], v[164:167], v[194:197], v[22:25]
	v_mfma_f32_16x16x32_bf16 v[26:29], v[172:175], v[194:197], v[26:29]
	s_setprio 0
	s_barrier
	v_or_b32_e32 v13, 0x18000, v12
	v_add_u32_e32 v34, 0x18400, v12
	ds_read_b128 v[40:43], v13
	ds_read_b128 v[44:47], v34
	v_add_u32_e32 v13, 0x18800, v12
	v_add_u32_e32 v34, 0x18c00, v12
	ds_read_b128 v[80:83], v13
	ds_read_b128 v[84:87], v34
	v_or_b32_e32 v13, 0x1c000, v12
	v_add_u32_e32 v34, 0x1c400, v12
	ds_read_b128 v[160:163], v13
	ds_read_b128 v[164:167], v34
	v_add_u32_e32 v13, 0x1c800, v12
	v_add_u32_e32 v34, 0x1cc00, v12
	ds_read_b128 v[168:171], v13
	ds_read_b128 v[172:175], v34
	s_add_u32 s6, s6, 0x40000
	s_addc_u32 s7, s7, 0
	s_mov_b32 m0, s28
	ds_read_b128 v[186:189], v11 offset:32768
	ds_read_b128 v[194:197], v11 offset:33792
	ds_read_b128 v[198:201], v11 offset:34816
	ds_read_b128 v[202:205], v11 offset:35840
	ds_read_b128 v[220:223], v11 offset:36864
	ds_read_b128 v[224:227], v11 offset:37888
	ds_read_b128 v[228:231], v11 offset:38912
	ds_read_b128 v[232:235], v11 offset:39936
	global_load_lds_dwordx4 v176, s[6:7]
	s_mov_b32 m0, s29
	s_nop 0
	global_load_lds_dwordx4 v0, s[6:7]
	s_waitcnt vmcnt(8)
	s_waitcnt lgkmcnt(0)
	s_barrier
	s_setprio 1
	s_waitcnt lgkmcnt(0)
	v_mfma_f32_16x16x32_bf16 v[156:159], v[40:43], v[186:189], v[156:159]
	v_mfma_f32_16x16x32_bf16 v[152:155], v[80:83], v[186:189], v[152:155]
	v_mfma_f32_16x16x32_bf16 v[140:143], v[40:43], v[198:201], v[140:143]
	v_mfma_f32_16x16x32_bf16 v[136:139], v[80:83], v[198:201], v[136:139]
	v_mfma_f32_16x16x32_bf16 v[124:127], v[40:43], v[220:223], v[124:127]
	v_mfma_f32_16x16x32_bf16 v[120:123], v[80:83], v[220:223], v[120:123]
	v_mfma_f32_16x16x32_bf16 v[108:111], v[40:43], v[228:231], v[108:111]
	v_mfma_f32_16x16x32_bf16 v[104:107], v[80:83], v[228:231], v[104:107]
	v_mfma_f32_16x16x32_bf16 v[156:159], v[44:47], v[194:197], v[156:159]
	v_mfma_f32_16x16x32_bf16 v[152:155], v[84:87], v[194:197], v[152:155]
	v_mfma_f32_16x16x32_bf16 v[140:143], v[44:47], v[202:205], v[140:143]
	v_mfma_f32_16x16x32_bf16 v[136:139], v[84:87], v[202:205], v[136:139]
	v_mfma_f32_16x16x32_bf16 v[124:127], v[44:47], v[224:227], v[124:127]
	v_mfma_f32_16x16x32_bf16 v[120:123], v[84:87], v[224:227], v[120:123]
	v_mfma_f32_16x16x32_bf16 v[108:111], v[44:47], v[232:235], v[108:111]
	v_mfma_f32_16x16x32_bf16 v[104:107], v[84:87], v[232:235], v[104:107]
	s_setprio 0
	s_setprio 1
	v_mfma_f32_16x16x32_bf16 v[148:151], v[160:163], v[186:189], v[148:151]
	v_mfma_f32_16x16x32_bf16 v[144:147], v[168:171], v[186:189], v[144:147]
	v_mfma_f32_16x16x32_bf16 v[132:135], v[160:163], v[198:201], v[132:135]
	v_mfma_f32_16x16x32_bf16 v[128:131], v[168:171], v[198:201], v[128:131]
	v_mfma_f32_16x16x32_bf16 v[116:119], v[160:163], v[220:223], v[116:119]
	v_mfma_f32_16x16x32_bf16 v[112:115], v[168:171], v[220:223], v[112:115]
	v_mfma_f32_16x16x32_bf16 v[100:103], v[160:163], v[228:231], v[100:103]
	v_mfma_f32_16x16x32_bf16 v[96:99], v[168:171], v[228:231], v[96:99]
	v_mfma_f32_16x16x32_bf16 v[148:151], v[164:167], v[194:197], v[148:151]
	v_mfma_f32_16x16x32_bf16 v[144:147], v[172:175], v[194:197], v[144:147]
	v_mfma_f32_16x16x32_bf16 v[132:135], v[164:167], v[202:205], v[132:135]
	v_mfma_f32_16x16x32_bf16 v[128:131], v[172:175], v[202:205], v[128:131]
	v_mfma_f32_16x16x32_bf16 v[116:119], v[164:167], v[224:227], v[116:119]
	v_mfma_f32_16x16x32_bf16 v[112:115], v[172:175], v[224:227], v[112:115]
	v_mfma_f32_16x16x32_bf16 v[100:103], v[164:167], v[232:235], v[100:103]
	v_mfma_f32_16x16x32_bf16 v[96:99], v[172:175], v[232:235], v[96:99]
	s_setprio 0
	s_barrier
	s_mov_b32 m0, s30
	v_lshl_add_u64 v[34:35], v[190:191], 0, s[0:1]
	s_add_u32 s2, s2, 0x40080
	ds_read_b128 v[186:189], v11 offset:49152
	ds_read_b128 v[194:197], v11 offset:50176
	ds_read_b128 v[198:201], v11 offset:51200
	ds_read_b128 v[202:205], v11 offset:52224
	ds_read_b128 v[220:223], v11 offset:53248
	ds_read_b128 v[224:227], v11 offset:54272
	ds_read_b128 v[228:231], v11 offset:55296
	ds_read_b128 v[232:235], v11 offset:56320
	global_load_lds_dwordx4 v[34:35], off
	v_lshl_add_u64 v[34:35], v[214:215], 0, s[0:1]
	s_mov_b32 m0, s31
	s_addc_u32 s3, s3, 0
	global_load_lds_dwordx4 v[34:35], off
	s_mov_b32 m0, s42
	s_nop 0
	global_load_lds_dwordx4 v176, s[2:3]
	s_mov_b32 m0, s43
	s_nop 0
	global_load_lds_dwordx4 v0, s[2:3]
	v_lshl_add_u64 v[34:35], v[236:237], 0, s[0:1]
	s_mov_b32 m0, s34
	s_nop 0
	global_load_lds_dwordx4 v[34:35], off
	v_lshl_add_u64 v[34:35], v[238:239], 0, s[0:1]
	s_mov_b32 m0, s35
	s_nop 0
	global_load_lds_dwordx4 v[34:35], off
	s_waitcnt vmcnt(8)
	s_waitcnt lgkmcnt(0)
	s_barrier
	s_setprio 1
	s_waitcnt lgkmcnt(0)
	v_mfma_f32_16x16x32_bf16 v[92:95], v[40:43], v[186:189], v[92:95]
	v_mfma_f32_16x16x32_bf16 v[76:79], v[40:43], v[198:201], v[76:79]
	v_mfma_f32_16x16x32_bf16 v[60:63], v[40:43], v[220:223], v[60:63]
	v_mfma_f32_16x16x32_bf16 v[14:17], v[40:43], v[228:231], v[14:17]
	v_mfma_f32_16x16x32_bf16 v[92:95], v[44:47], v[194:197], v[92:95]
	v_mfma_f32_16x16x32_bf16 v[88:91], v[80:83], v[186:189], v[88:91]
	v_mfma_f32_16x16x32_bf16 v[76:79], v[44:47], v[202:205], v[76:79]
	v_mfma_f32_16x16x32_bf16 v[72:75], v[80:83], v[198:201], v[72:75]
	v_mfma_f32_16x16x32_bf16 v[60:63], v[44:47], v[224:227], v[60:63]
	v_mfma_f32_16x16x32_bf16 v[56:59], v[80:83], v[220:223], v[56:59]
	v_mfma_f32_16x16x32_bf16 v[44:47], v[44:47], v[232:235], v[14:17]
	v_mfma_f32_16x16x32_bf16 v[14:17], v[80:83], v[228:231], v[18:21]
	v_mfma_f32_16x16x32_bf16 v[88:91], v[84:87], v[194:197], v[88:91]
	v_mfma_f32_16x16x32_bf16 v[72:75], v[84:87], v[202:205], v[72:75]
	v_mfma_f32_16x16x32_bf16 v[56:59], v[84:87], v[224:227], v[56:59]
	v_mfma_f32_16x16x32_bf16 v[40:43], v[84:87], v[232:235], v[14:17]
	s_setprio 0
	s_setprio 1
	v_mfma_f32_16x16x32_bf16 v[14:17], v[160:163], v[186:189], v[22:25]
	v_mfma_f32_16x16x32_bf16 v[84:87], v[164:167], v[194:197], v[14:17]
	v_mfma_f32_16x16x32_bf16 v[14:17], v[168:171], v[186:189], v[26:29]
	v_mfma_f32_16x16x32_bf16 v[80:83], v[172:175], v[194:197], v[14:17]
	v_mfma_f32_16x16x32_bf16 v[14:17], v[160:163], v[198:201], v[68:71]
	v_mfma_f32_16x16x32_bf16 v[68:71], v[164:167], v[202:205], v[14:17]
	v_mfma_f32_16x16x32_bf16 v[14:17], v[168:171], v[198:201], v[64:67]
	v_mfma_f32_16x16x32_bf16 v[64:67], v[172:175], v[202:205], v[14:17]
	v_mfma_f32_16x16x32_bf16 v[14:17], v[160:163], v[220:223], v[52:55]
	v_mfma_f32_16x16x32_bf16 v[52:55], v[164:167], v[224:227], v[14:17]
	v_mfma_f32_16x16x32_bf16 v[14:17], v[168:171], v[220:223], v[48:51]
	v_mfma_f32_16x16x32_bf16 v[48:51], v[172:175], v[224:227], v[14:17]
	v_mfma_f32_16x16x32_bf16 v[14:17], v[160:163], v[228:231], v[36:39]
	v_mfma_f32_16x16x32_bf16 v[36:39], v[164:167], v[232:235], v[14:17]
	v_mfma_f32_16x16x32_bf16 v[14:17], v[168:171], v[228:231], v[30:33]
	v_mfma_f32_16x16x32_bf16 v[32:35], v[172:175], v[232:235], v[14:17]
	s_setprio 0
	s_barrier
	s_add_i32 s95, s95, 2
	s_add_u32 s90, s90, 0x100
	s_addc_u32 s91, s91, 0
	s_cmp_gt_u32 s95, 13
	s_cbranch_scc0 .LBB0_326
	s_add_u32 s2, s75, 0xffffff00
	s_addc_u32 s3, s83, -1
	s_andn2_b64 vcc, exec, s[38:39]
	s_cbranch_vccnz .LBB0_317
	v_mov_b32_e32 v32, 0
	s_mov_b32 s9, s4
	s_mov_b32 s82, s84
	s_mov_b64 s[40:41], s[88:89]
	s_mov_b32 s72, s74
	v_mov_b32_e32 v33, v32
	v_mov_b32_e32 v34, v32
	v_mov_b32_e32 v35, v32
	v_mov_b32_e32 v36, v32
	v_mov_b32_e32 v37, v32
	v_mov_b32_e32 v38, v32
	v_mov_b32_e32 v39, v32
	v_mov_b32_e32 v48, v32
	v_mov_b32_e32 v49, v32
	v_mov_b32_e32 v50, v32
	v_mov_b32_e32 v51, v32
	v_mov_b32_e32 v52, v32
	v_mov_b32_e32 v53, v32
	v_mov_b32_e32 v54, v32
	v_mov_b32_e32 v55, v32
	v_mov_b32_e32 v64, v32
	v_mov_b32_e32 v65, v32
	v_mov_b32_e32 v66, v32
	v_mov_b32_e32 v67, v32
	v_mov_b32_e32 v68, v32
	v_mov_b32_e32 v69, v32
	v_mov_b32_e32 v70, v32
	v_mov_b32_e32 v71, v32
	v_mov_b32_e32 v80, v32
	v_mov_b32_e32 v81, v32
	v_mov_b32_e32 v82, v32
	v_mov_b32_e32 v83, v32
	v_mov_b32_e32 v84, v32
	v_mov_b32_e32 v85, v32
	v_mov_b32_e32 v86, v32
	v_mov_b32_e32 v87, v32
	v_mov_b32_e32 v40, v32
	v_mov_b32_e32 v41, v32
	v_mov_b32_e32 v42, v32
	v_mov_b32_e32 v43, v32
	v_mov_b32_e32 v44, v32
	v_mov_b32_e32 v45, v32
	v_mov_b32_e32 v46, v32
	v_mov_b32_e32 v47, v32
	v_mov_b32_e32 v56, v32
	v_mov_b32_e32 v57, v32
	v_mov_b32_e32 v58, v32
	v_mov_b32_e32 v59, v32
	v_mov_b32_e32 v60, v32
	v_mov_b32_e32 v61, v32
	v_mov_b32_e32 v62, v32
	v_mov_b32_e32 v63, v32
	v_mov_b32_e32 v72, v32
	v_mov_b32_e32 v73, v32
	v_mov_b32_e32 v74, v32
	v_mov_b32_e32 v75, v32
	v_mov_b32_e32 v76, v32
	v_mov_b32_e32 v77, v32
	v_mov_b32_e32 v78, v32
	v_mov_b32_e32 v79, v32
	v_mov_b32_e32 v88, v32
	v_mov_b32_e32 v89, v32
	v_mov_b32_e32 v90, v32
	v_mov_b32_e32 v91, v32
	v_mov_b32_e32 v92, v32
	v_mov_b32_e32 v93, v32
	v_mov_b32_e32 v94, v32
	v_mov_b32_e32 v95, v32
	v_mov_b32_e32 v96, v32
	v_mov_b32_e32 v97, v32
	v_mov_b32_e32 v98, v32
	v_mov_b32_e32 v99, v32
	v_mov_b32_e32 v100, v32
	v_mov_b32_e32 v101, v32
	v_mov_b32_e32 v102, v32
	v_mov_b32_e32 v103, v32
	v_mov_b32_e32 v112, v32
	v_mov_b32_e32 v113, v32
	v_mov_b32_e32 v114, v32
	v_mov_b32_e32 v115, v32
	v_mov_b32_e32 v116, v32
	v_mov_b32_e32 v117, v32
	v_mov_b32_e32 v118, v32
	v_mov_b32_e32 v119, v32
	v_mov_b32_e32 v128, v32
	v_mov_b32_e32 v129, v32
	v_mov_b32_e32 v130, v32
	v_mov_b32_e32 v131, v32
	v_mov_b32_e32 v132, v32
	v_mov_b32_e32 v133, v32
	v_mov_b32_e32 v134, v32
	v_mov_b32_e32 v135, v32
	v_mov_b32_e32 v144, v32
	v_mov_b32_e32 v145, v32
	v_mov_b32_e32 v146, v32
	v_mov_b32_e32 v147, v32
	v_mov_b32_e32 v148, v32
	v_mov_b32_e32 v149, v32
	v_mov_b32_e32 v150, v32
	v_mov_b32_e32 v151, v32
	v_mov_b32_e32 v104, v32
	v_mov_b32_e32 v105, v32
	v_mov_b32_e32 v106, v32
	v_mov_b32_e32 v107, v32
	v_mov_b32_e32 v108, v32
	v_mov_b32_e32 v109, v32
	v_mov_b32_e32 v110, v32
	v_mov_b32_e32 v111, v32
	v_mov_b32_e32 v120, v32
	v_mov_b32_e32 v121, v32
	v_mov_b32_e32 v122, v32
	v_mov_b32_e32 v123, v32
	v_mov_b32_e32 v124, v32
	v_mov_b32_e32 v125, v32
	v_mov_b32_e32 v126, v32
	v_mov_b32_e32 v127, v32
	v_mov_b32_e32 v136, v32
	v_mov_b32_e32 v137, v32
	v_mov_b32_e32 v138, v32
	v_mov_b32_e32 v139, v32
	v_mov_b32_e32 v140, v32
	v_mov_b32_e32 v141, v32
	v_mov_b32_e32 v142, v32
	v_mov_b32_e32 v143, v32
	v_mov_b32_e32 v152, v32
	v_mov_b32_e32 v153, v32
	v_mov_b32_e32 v154, v32
	v_mov_b32_e32 v155, v32
	v_mov_b32_e32 v156, v32
	v_mov_b32_e32 v157, v32
	v_mov_b32_e32 v158, v32
	v_mov_b32_e32 v159, v32
	s_andn2_b64 vcc, exec, s[36:37]
	s_cbranch_vccnz .LBB0_318

.LBB0_438:
	v_or_b32_e32 v143, 0x10000, v140
	v_add_u32_e32 v148, 0x10400, v140
	ds_read_b128 v[144:147], v143
	ds_read_b128 v[148:151], v148
	v_add_u32_e32 v143, 0x10800, v140
	v_add_u32_e32 v156, 0x10c00, v140
	ds_read_b128 v[152:155], v143
	ds_read_b128 v[156:159], v156
	v_or_b32_e32 v143, 0x14000, v140
	v_add_u32_e32 v164, 0x14400, v140
	ds_read_b128 v[160:163], v143
	ds_read_b128 v[164:167], v164
	v_add_u32_e32 v143, 0x14800, v140
	v_add_u32_e32 v172, 0x14c00, v140
	ds_read_b128 v[168:171], v143
	ds_read_b128 v[172:175], v172
	s_add_u32 s2, s90, 0xfffc0080
	s_addc_u32 s3, s91, -1
	s_cmp_eq_u32 s95, 12
	s_cselect_b32 s7, s8, s3
	s_cselect_b32 s6, s9, s2
	s_cselect_b32 s3, s83, s94
	s_cselect_b32 s2, s85, s92
	s_add_i32 m0, s20, 0xc000
	ds_read_b128 v[186:189], v139
	ds_read_b128 v[190:193], v139 offset:1024
	ds_read_b128 v[194:197], v139 offset:2048
	ds_read_b128 v[198:201], v139 offset:3072
	ds_read_b128 v[202:205], v139 offset:4096
	ds_read_b128 v[220:223], v139 offset:5120
	ds_read_b128 v[224:227], v139 offset:6144
	ds_read_b128 v[228:231], v139 offset:7168
	global_load_lds_dwordx4 v134, s[90:91]
	s_add_i32 m0, s20, 0xe000
	s_nop 0
	global_load_lds_dwordx4 v136, s[90:91]
	s_waitcnt vmcnt(8)
	s_waitcnt lgkmcnt(0)
	s_barrier
	s_setprio 1
	s_waitcnt lgkmcnt(0)
	v_mfma_f32_16x16x32_bf16 v[124:127], v[144:147], v[186:189], v[124:127]
	v_mfma_f32_16x16x32_bf16 v[120:123], v[152:155], v[186:189], v[120:123]
	v_mfma_f32_16x16x32_bf16 v[116:119], v[144:147], v[194:197], v[116:119]
	v_mfma_f32_16x16x32_bf16 v[112:115], v[152:155], v[194:197], v[112:115]
	v_mfma_f32_16x16x32_bf16 v[100:103], v[144:147], v[202:205], v[100:103]
	v_mfma_f32_16x16x32_bf16 v[96:99], v[152:155], v[202:205], v[96:99]
	v_mfma_f32_16x16x32_bf16 v[84:87], v[144:147], v[224:227], v[84:87]
	v_mfma_f32_16x16x32_bf16 v[80:83], v[152:155], v[224:227], v[80:83]
	v_mfma_f32_16x16x32_bf16 v[124:127], v[148:151], v[190:193], v[124:127]
	v_mfma_f32_16x16x32_bf16 v[120:123], v[156:159], v[190:193], v[120:123]
	v_mfma_f32_16x16x32_bf16 v[116:119], v[148:151], v[198:201], v[116:119]
	v_mfma_f32_16x16x32_bf16 v[112:115], v[156:159], v[198:201], v[112:115]
	v_mfma_f32_16x16x32_bf16 v[100:103], v[148:151], v[220:223], v[100:103]
	v_mfma_f32_16x16x32_bf16 v[96:99], v[156:159], v[220:223], v[96:99]
	v_mfma_f32_16x16x32_bf16 v[84:87], v[148:151], v[228:231], v[84:87]
	v_mfma_f32_16x16x32_bf16 v[80:83], v[156:159], v[228:231], v[80:83]
	s_setprio 0
	s_setprio 1
	v_mfma_f32_16x16x32_bf16 v[108:111], v[160:163], v[186:189], v[108:111]
	v_mfma_f32_16x16x32_bf16 v[104:107], v[168:171], v[186:189], v[104:107]
	v_mfma_f32_16x16x32_bf16 v[92:95], v[160:163], v[194:197], v[92:95]
	v_mfma_f32_16x16x32_bf16 v[88:91], v[168:171], v[194:197], v[88:91]
	v_mfma_f32_16x16x32_bf16 v[76:79], v[160:163], v[202:205], v[76:79]
	v_mfma_f32_16x16x32_bf16 v[72:75], v[168:171], v[202:205], v[72:75]
	v_mfma_f32_16x16x32_bf16 v[68:71], v[160:163], v[224:227], v[68:71]
	v_mfma_f32_16x16x32_bf16 v[64:67], v[168:171], v[224:227], v[64:67]
	v_mfma_f32_16x16x32_bf16 v[108:111], v[164:167], v[190:193], v[108:111]
	v_mfma_f32_16x16x32_bf16 v[104:107], v[172:175], v[190:193], v[104:107]
	v_mfma_f32_16x16x32_bf16 v[92:95], v[164:167], v[198:201], v[92:95]
	v_mfma_f32_16x16x32_bf16 v[88:91], v[172:175], v[198:201], v[88:91]
	v_mfma_f32_16x16x32_bf16 v[76:79], v[164:167], v[220:223], v[76:79]
	v_mfma_f32_16x16x32_bf16 v[72:75], v[172:175], v[220:223], v[72:75]
	v_mfma_f32_16x16x32_bf16 v[68:71], v[164:167], v[228:231], v[68:71]
	v_mfma_f32_16x16x32_bf16 v[64:67], v[172:175], v[228:231], v[64:67]
	s_setprio 0
	s_barrier
	s_mov_b32 m0, s5
	v_lshl_add_u64 v[232:233], s[2:3], 0, v[176:177]
	s_add_u32 s96, s2, 0x40000
	ds_read_b128 v[186:189], v139 offset:16384
	ds_read_b128 v[190:193], v139 offset:17408
	ds_read_b128 v[194:197], v139 offset:18432
	ds_read_b128 v[198:201], v139 offset:19456
	ds_read_b128 v[202:205], v139 offset:20480
	ds_read_b128 v[220:223], v139 offset:21504
	ds_read_b128 v[224:227], v139 offset:22528
	ds_read_b128 v[228:231], v139 offset:23552
	global_load_lds_dwordx4 v[232:233], off
	v_lshl_add_u64 v[234:235], s[2:3], 0, v[128:129]
	s_mov_b32 m0, s22
	s_addc_u32 s97, s3, 0
	global_load_lds_dwordx4 v[234:235], off
	s_mov_b32 m0, s23
	v_lshl_add_u64 v[238:239], s[6:7], 0, v[130:131]
	global_load_lds_dwordx4 v176, s[96:97]
	s_mov_b32 m0, s24
	s_nop 0
	global_load_lds_dwordx4 v128, s[96:97]
	v_lshl_add_u64 v[236:237], s[6:7], 0, v[132:133]
	s_mov_b32 m0, s20
	s_nop 0
	global_load_lds_dwordx4 v[236:237], off
	s_mov_b32 m0, s25
	s_nop 0
	global_load_lds_dwordx4 v[238:239], off
	s_waitcnt vmcnt(8)
	s_waitcnt lgkmcnt(0)
	s_barrier
	s_setprio 1
	s_waitcnt lgkmcnt(0)
	v_mfma_f32_16x16x32_bf16 v[60:63], v[144:147], v[186:189], v[60:63]
	v_mfma_f32_16x16x32_bf16 v[56:59], v[152:155], v[186:189], v[56:59]
	v_mfma_f32_16x16x32_bf16 v[52:55], v[144:147], v[194:197], v[52:55]
	v_mfma_f32_16x16x32_bf16 v[48:51], v[152:155], v[194:197], v[48:51]
	v_mfma_f32_16x16x32_bf16 v[36:39], v[144:147], v[202:205], v[36:39]
	v_mfma_f32_16x16x32_bf16 v[32:35], v[152:155], v[202:205], v[32:35]
	v_mfma_f32_16x16x32_bf16 v[20:23], v[144:147], v[224:227], v[20:23]
	v_mfma_f32_16x16x32_bf16 v[16:19], v[152:155], v[224:227], v[16:19]
	v_mfma_f32_16x16x32_bf16 v[60:63], v[148:151], v[190:193], v[60:63]
	v_mfma_f32_16x16x32_bf16 v[56:59], v[156:159], v[190:193], v[56:59]
	v_mfma_f32_16x16x32_bf16 v[52:55], v[148:151], v[198:201], v[52:55]
	v_mfma_f32_16x16x32_bf16 v[48:51], v[156:159], v[198:201], v[48:51]
	v_mfma_f32_16x16x32_bf16 v[36:39], v[148:151], v[220:223], v[36:39]
	v_mfma_f32_16x16x32_bf16 v[32:35], v[156:159], v[220:223], v[32:35]
	v_mfma_f32_16x16x32_bf16 v[20:23], v[148:151], v[228:231], v[20:23]
	v_mfma_f32_16x16x32_bf16 v[16:19], v[156:159], v[228:231], v[16:19]
	s_setprio 0
	s_setprio 1
	v_mfma_f32_16x16x32_bf16 v[44:47], v[160:163], v[186:189], v[44:47]
	v_mfma_f32_16x16x32_bf16 v[40:43], v[168:171], v[186:189], v[40:43]
	v_mfma_f32_16x16x32_bf16 v[28:31], v[160:163], v[194:197], v[28:31]
	v_mfma_f32_16x16x32_bf16 v[24:27], v[168:171], v[194:197], v[24:27]
	v_mfma_f32_16x16x32_bf16 v[12:15], v[160:163], v[202:205], v[12:15]
	v_mfma_f32_16x16x32_bf16 v[8:11], v[168:171], v[202:205], v[8:11]
	v_mfma_f32_16x16x32_bf16 v[4:7], v[160:163], v[224:227], v[4:7]
	v_mfma_f32_16x16x32_bf16 v[0:3], v[168:171], v[224:227], v[0:3]
	v_mfma_f32_16x16x32_bf16 v[44:47], v[164:167], v[190:193], v[44:47]
	v_mfma_f32_16x16x32_bf16 v[40:43], v[172:175], v[190:193], v[40:43]
	v_mfma_f32_16x16x32_bf16 v[28:31], v[164:167], v[198:201], v[28:31]
	v_mfma_f32_16x16x32_bf16 v[24:27], v[172:175], v[198:201], v[24:27]
	v_mfma_f32_16x16x32_bf16 v[12:15], v[164:167], v[220:223], v[12:15]
	v_mfma_f32_16x16x32_bf16 v[8:11], v[172:175], v[220:223], v[8:11]
	v_mfma_f32_16x16x32_bf16 v[4:7], v[164:167], v[228:231], v[4:7]
	v_mfma_f32_16x16x32_bf16 v[0:3], v[172:175], v[228:231], v[0:3]
	s_setprio 0
	s_barrier
	v_or_b32_e32 v143, 0x18000, v140
	v_add_u32_e32 v148, 0x18400, v140
	ds_read_b128 v[144:147], v143
	ds_read_b128 v[148:151], v148
	v_add_u32_e32 v143, 0x18800, v140
	v_add_u32_e32 v156, 0x18c00, v140
	ds_read_b128 v[152:155], v143
	ds_read_b128 v[156:159], v156
	v_or_b32_e32 v143, 0x1c000, v140
	v_add_u32_e32 v164, 0x1c400, v140
	ds_read_b128 v[160:163], v143
	ds_read_b128 v[164:167], v164
	v_add_u32_e32 v143, 0x1c800, v140
	v_add_u32_e32 v172, 0x1cc00, v140
	ds_read_b128 v[168:171], v143
	ds_read_b128 v[172:175], v172
	s_add_u32 s6, s6, 0x40000
	s_addc_u32 s7, s7, 0
	s_mov_b32 m0, s26
	ds_read_b128 v[186:189], v139 offset:32768
	ds_read_b128 v[190:193], v139 offset:33792
	ds_read_b128 v[194:197], v139 offset:34816
	ds_read_b128 v[198:201], v139 offset:35840
	ds_read_b128 v[202:205], v139 offset:36864
	ds_read_b128 v[220:223], v139 offset:37888
	ds_read_b128 v[224:227], v139 offset:38912
	ds_read_b128 v[228:231], v139 offset:39936
	global_load_lds_dwordx4 v132, s[6:7]
	v_lshl_add_u64 v[240:241], s[6:7], 0, v[130:131]
	s_mov_b32 m0, s27
	s_nop 0
	global_load_lds_dwordx4 v[240:241], off
	s_waitcnt vmcnt(8)
	s_waitcnt lgkmcnt(0)
	s_barrier
	s_setprio 1
	s_waitcnt lgkmcnt(0)
	v_mfma_f32_16x16x32_bf16 v[124:127], v[144:147], v[186:189], v[124:127]
	v_mfma_f32_16x16x32_bf16 v[120:123], v[152:155], v[186:189], v[120:123]
	v_mfma_f32_16x16x32_bf16 v[116:119], v[144:147], v[194:197], v[116:119]
	v_mfma_f32_16x16x32_bf16 v[112:115], v[152:155], v[194:197], v[112:115]
	v_mfma_f32_16x16x32_bf16 v[100:103], v[144:147], v[202:205], v[100:103]
	v_mfma_f32_16x16x32_bf16 v[96:99], v[152:155], v[202:205], v[96:99]
	v_mfma_f32_16x16x32_bf16 v[84:87], v[144:147], v[224:227], v[84:87]
	v_mfma_f32_16x16x32_bf16 v[80:83], v[152:155], v[224:227], v[80:83]
	v_mfma_f32_16x16x32_bf16 v[124:127], v[148:151], v[190:193], v[124:127]
	v_mfma_f32_16x16x32_bf16 v[120:123], v[156:159], v[190:193], v[120:123]
	v_mfma_f32_16x16x32_bf16 v[116:119], v[148:151], v[198:201], v[116:119]
	v_mfma_f32_16x16x32_bf16 v[112:115], v[156:159], v[198:201], v[112:115]
	v_mfma_f32_16x16x32_bf16 v[100:103], v[148:151], v[220:223], v[100:103]
	v_mfma_f32_16x16x32_bf16 v[96:99], v[156:159], v[220:223], v[96:99]
	v_mfma_f32_16x16x32_bf16 v[84:87], v[148:151], v[228:231], v[84:87]
	v_mfma_f32_16x16x32_bf16 v[80:83], v[156:159], v[228:231], v[80:83]
	s_setprio 0
	s_setprio 1
	v_mfma_f32_16x16x32_bf16 v[108:111], v[160:163], v[186:189], v[108:111]
	v_mfma_f32_16x16x32_bf16 v[104:107], v[168:171], v[186:189], v[104:107]
	v_mfma_f32_16x16x32_bf16 v[92:95], v[160:163], v[194:197], v[92:95]
	v_mfma_f32_16x16x32_bf16 v[88:91], v[168:171], v[194:197], v[88:91]
	v_mfma_f32_16x16x32_bf16 v[76:79], v[160:163], v[202:205], v[76:79]
	v_mfma_f32_16x16x32_bf16 v[72:75], v[168:171], v[202:205], v[72:75]
	v_mfma_f32_16x16x32_bf16 v[68:71], v[160:163], v[224:227], v[68:71]
	v_mfma_f32_16x16x32_bf16 v[64:67], v[168:171], v[224:227], v[64:67]
	v_mfma_f32_16x16x32_bf16 v[108:111], v[164:167], v[190:193], v[108:111]
	v_mfma_f32_16x16x32_bf16 v[104:107], v[172:175], v[190:193], v[104:107]
	v_mfma_f32_16x16x32_bf16 v[92:95], v[164:167], v[198:201], v[92:95]
	v_mfma_f32_16x16x32_bf16 v[88:91], v[172:175], v[198:201], v[88:91]
	v_mfma_f32_16x16x32_bf16 v[76:79], v[164:167], v[220:223], v[76:79]
	v_mfma_f32_16x16x32_bf16 v[72:75], v[172:175], v[220:223], v[72:75]
	v_mfma_f32_16x16x32_bf16 v[68:71], v[164:167], v[228:231], v[68:71]
	v_mfma_f32_16x16x32_bf16 v[64:67], v[172:175], v[228:231], v[64:67]
	s_setprio 0
	s_barrier
	s_mov_b32 m0, s28
	v_lshl_add_u64 v[232:233], v[232:233], 0, s[0:1]
	s_add_u32 s2, s2, 0x40080
	ds_read_b128 v[186:189], v139 offset:49152
	ds_read_b128 v[190:193], v139 offset:50176
	ds_read_b128 v[194:197], v139 offset:51200
	ds_read_b128 v[198:201], v139 offset:52224
	ds_read_b128 v[202:205], v139 offset:53248
	ds_read_b128 v[220:223], v139 offset:54272
	ds_read_b128 v[224:227], v139 offset:55296
	ds_read_b128 v[228:231], v139 offset:56320
	global_load_lds_dwordx4 v[232:233], off
	v_lshl_add_u64 v[232:233], v[234:235], 0, s[0:1]
	s_mov_b32 m0, s29
	s_addc_u32 s3, s3, 0
	global_load_lds_dwordx4 v[232:233], off
	s_mov_b32 m0, s34
	s_nop 0
	global_load_lds_dwordx4 v176, s[2:3]
	s_mov_b32 m0, s35
	s_nop 0
	global_load_lds_dwordx4 v128, s[2:3]
	v_lshl_add_u64 v[232:233], v[236:237], 0, s[0:1]
	s_mov_b32 m0, s30
	s_nop 0
	global_load_lds_dwordx4 v[232:233], off
	v_lshl_add_u64 v[232:233], v[238:239], 0, s[0:1]
	s_mov_b32 m0, s31
	s_nop 0
	global_load_lds_dwordx4 v[232:233], off
	s_waitcnt vmcnt(8)
	s_waitcnt lgkmcnt(0)
	s_barrier
	s_setprio 1
	s_waitcnt lgkmcnt(0)
	v_mfma_f32_16x16x32_bf16 v[60:63], v[144:147], v[186:189], v[60:63]
	v_mfma_f32_16x16x32_bf16 v[56:59], v[152:155], v[186:189], v[56:59]
	v_mfma_f32_16x16x32_bf16 v[52:55], v[144:147], v[194:197], v[52:55]
	v_mfma_f32_16x16x32_bf16 v[48:51], v[152:155], v[194:197], v[48:51]
	v_mfma_f32_16x16x32_bf16 v[36:39], v[144:147], v[202:205], v[36:39]
	v_mfma_f32_16x16x32_bf16 v[32:35], v[152:155], v[202:205], v[32:35]
	v_mfma_f32_16x16x32_bf16 v[20:23], v[144:147], v[224:227], v[20:23]
	v_mfma_f32_16x16x32_bf16 v[16:19], v[152:155], v[224:227], v[16:19]
	v_mfma_f32_16x16x32_bf16 v[60:63], v[148:151], v[190:193], v[60:63]
	v_mfma_f32_16x16x32_bf16 v[56:59], v[156:159], v[190:193], v[56:59]
	v_mfma_f32_16x16x32_bf16 v[52:55], v[148:151], v[198:201], v[52:55]
	v_mfma_f32_16x16x32_bf16 v[48:51], v[156:159], v[198:201], v[48:51]
	v_mfma_f32_16x16x32_bf16 v[36:39], v[148:151], v[220:223], v[36:39]
	v_mfma_f32_16x16x32_bf16 v[32:35], v[156:159], v[220:223], v[32:35]
	v_mfma_f32_16x16x32_bf16 v[20:23], v[148:151], v[228:231], v[20:23]
	v_mfma_f32_16x16x32_bf16 v[16:19], v[156:159], v[228:231], v[16:19]
	s_setprio 0
	s_setprio 1
	v_mfma_f32_16x16x32_bf16 v[44:47], v[160:163], v[186:189], v[44:47]
	v_mfma_f32_16x16x32_bf16 v[40:43], v[168:171], v[186:189], v[40:43]
	v_mfma_f32_16x16x32_bf16 v[28:31], v[160:163], v[194:197], v[28:31]
	v_mfma_f32_16x16x32_bf16 v[24:27], v[168:171], v[194:197], v[24:27]
	v_mfma_f32_16x16x32_bf16 v[12:15], v[160:163], v[202:205], v[12:15]
	v_mfma_f32_16x16x32_bf16 v[8:11], v[168:171], v[202:205], v[8:11]
	v_mfma_f32_16x16x32_bf16 v[4:7], v[160:163], v[224:227], v[4:7]
	v_mfma_f32_16x16x32_bf16 v[0:3], v[168:171], v[224:227], v[0:3]
	v_mfma_f32_16x16x32_bf16 v[44:47], v[164:167], v[190:193], v[44:47]
	v_mfma_f32_16x16x32_bf16 v[40:43], v[172:175], v[190:193], v[40:43]
	v_mfma_f32_16x16x32_bf16 v[28:31], v[164:167], v[198:201], v[28:31]
	v_mfma_f32_16x16x32_bf16 v[24:27], v[172:175], v[198:201], v[24:27]
	v_mfma_f32_16x16x32_bf16 v[12:15], v[164:167], v[220:223], v[12:15]
	v_mfma_f32_16x16x32_bf16 v[8:11], v[172:175], v[220:223], v[8:11]
	v_mfma_f32_16x16x32_bf16 v[4:7], v[164:167], v[228:231], v[4:7]
	v_mfma_f32_16x16x32_bf16 v[0:3], v[172:175], v[228:231], v[0:3]
	s_setprio 0
	s_barrier
	s_add_i32 s95, s95, 2
	s_add_u32 s90, s90, 0x100
	s_addc_u32 s91, s91, 0
	s_add_u32 s92, s92, 0x100
	s_addc_u32 s94, s94, 0
	s_cmp_gt_u32 s95, 13
	s_cbranch_scc0 .LBB0_438
	s_and_b64 vcc, exec, s[74:75]
	s_cbranch_vccz .LBB0_441
	s_barrier

.LBB0_462:
	v_or_b32_e32 v147, 0x10000, v145
	v_add_u32_e32 v152, 0x10400, v145
	ds_read_b128 v[148:151], v147
	ds_read_b128 v[152:155], v152
	v_add_u32_e32 v147, 0x10800, v145
	v_add_u32_e32 v160, 0x10c00, v145
	ds_read_b128 v[156:159], v147
	ds_read_b128 v[160:163], v160
	v_or_b32_e32 v147, 0x14000, v145
	v_add_u32_e32 v168, 0x14400, v145
	ds_read_b128 v[164:167], v147
	ds_read_b128 v[168:171], v168
	v_add_u32_e32 v147, 0x14800, v145
	v_add_u32_e32 v186, 0x14c00, v145
	ds_read_b128 v[172:175], v147
	ds_read_b128 v[186:189], v186
	s_add_u32 s2, s90, 0xfffc0080
	s_addc_u32 s3, s91, -1
	s_cmp_eq_u32 s95, 12
	s_cselect_b32 s7, s72, s3
	s_cselect_b32 s6, s75, s2
	s_cselect_b32 s3, s5, s94
	s_cselect_b32 s2, s85, s92
	s_add_i32 m0, s19, 0xc000
	ds_read_b128 v[190:193], v144
	ds_read_b128 v[194:197], v144 offset:1024
	ds_read_b128 v[198:201], v144 offset:2048
	ds_read_b128 v[202:205], v144 offset:3072
	ds_read_b128 v[220:223], v144 offset:4096
	ds_read_b128 v[224:227], v144 offset:5120
	ds_read_b128 v[228:231], v144 offset:6144
	ds_read_b128 v[232:235], v144 offset:7168
	global_load_lds_dwordx4 v138, s[90:91]
	s_add_i32 m0, s19, 0xe000
	s_nop 0
	global_load_lds_dwordx4 v140, s[90:91]
	s_waitcnt vmcnt(8)
	s_waitcnt lgkmcnt(0)
	s_barrier
	s_setprio 1
	s_waitcnt lgkmcnt(0)
	v_mfma_f32_16x16x32_bf16 v[124:127], v[148:151], v[190:193], v[124:127]
	v_mfma_f32_16x16x32_bf16 v[120:123], v[156:159], v[190:193], v[120:123]
	v_mfma_f32_16x16x32_bf16 v[116:119], v[148:151], v[198:201], v[116:119]
	v_mfma_f32_16x16x32_bf16 v[112:115], v[156:159], v[198:201], v[112:115]
	v_mfma_f32_16x16x32_bf16 v[100:103], v[148:151], v[220:223], v[100:103]
	v_mfma_f32_16x16x32_bf16 v[96:99], v[156:159], v[220:223], v[96:99]
	v_mfma_f32_16x16x32_bf16 v[84:87], v[148:151], v[228:231], v[84:87]
	v_mfma_f32_16x16x32_bf16 v[80:83], v[156:159], v[228:231], v[80:83]
	v_mfma_f32_16x16x32_bf16 v[124:127], v[152:155], v[194:197], v[124:127]
	v_mfma_f32_16x16x32_bf16 v[120:123], v[160:163], v[194:197], v[120:123]
	v_mfma_f32_16x16x32_bf16 v[116:119], v[152:155], v[202:205], v[116:119]
	v_mfma_f32_16x16x32_bf16 v[112:115], v[160:163], v[202:205], v[112:115]
	v_mfma_f32_16x16x32_bf16 v[100:103], v[152:155], v[224:227], v[100:103]
	v_mfma_f32_16x16x32_bf16 v[96:99], v[160:163], v[224:227], v[96:99]
	v_mfma_f32_16x16x32_bf16 v[84:87], v[152:155], v[232:235], v[84:87]
	v_mfma_f32_16x16x32_bf16 v[80:83], v[160:163], v[232:235], v[80:83]
	s_setprio 0
	s_setprio 1
	v_mfma_f32_16x16x32_bf16 v[108:111], v[164:167], v[190:193], v[108:111]
	v_mfma_f32_16x16x32_bf16 v[104:107], v[172:175], v[190:193], v[104:107]
	v_mfma_f32_16x16x32_bf16 v[92:95], v[164:167], v[198:201], v[92:95]
	v_mfma_f32_16x16x32_bf16 v[88:91], v[172:175], v[198:201], v[88:91]
	v_mfma_f32_16x16x32_bf16 v[76:79], v[164:167], v[220:223], v[76:79]
	v_mfma_f32_16x16x32_bf16 v[72:75], v[172:175], v[220:223], v[72:75]
	v_mfma_f32_16x16x32_bf16 v[68:71], v[164:167], v[228:231], v[68:71]
	v_mfma_f32_16x16x32_bf16 v[64:67], v[172:175], v[228:231], v[64:67]
	v_mfma_f32_16x16x32_bf16 v[108:111], v[168:171], v[194:197], v[108:111]
	v_mfma_f32_16x16x32_bf16 v[104:107], v[186:189], v[194:197], v[104:107]
	v_mfma_f32_16x16x32_bf16 v[92:95], v[168:171], v[202:205], v[92:95]
	v_mfma_f32_16x16x32_bf16 v[88:91], v[186:189], v[202:205], v[88:91]
	v_mfma_f32_16x16x32_bf16 v[76:79], v[168:171], v[224:227], v[76:79]
	v_mfma_f32_16x16x32_bf16 v[72:75], v[186:189], v[224:227], v[72:75]
	v_mfma_f32_16x16x32_bf16 v[68:71], v[168:171], v[232:235], v[68:71]
	v_mfma_f32_16x16x32_bf16 v[64:67], v[186:189], v[232:235], v[64:67]
	s_setprio 0
	s_barrier
	s_mov_b32 m0, s20
	v_lshl_add_u64 v[236:237], s[2:3], 0, v[130:131]
	s_add_u32 s96, s2, 0x40000
	ds_read_b128 v[190:193], v144 offset:16384
	ds_read_b128 v[194:197], v144 offset:17408
	ds_read_b128 v[198:201], v144 offset:18432
	ds_read_b128 v[202:205], v144 offset:19456
	ds_read_b128 v[220:223], v144 offset:20480
	ds_read_b128 v[224:227], v144 offset:21504
	ds_read_b128 v[228:231], v144 offset:22528
	ds_read_b128 v[232:235], v144 offset:23552
	global_load_lds_dwordx4 v[236:237], off
	v_lshl_add_u64 v[238:239], s[2:3], 0, v[134:135]
	s_mov_b32 m0, s21
	s_addc_u32 s97, s3, 0
	global_load_lds_dwordx4 v[238:239], off
	s_mov_b32 m0, s22
	v_lshl_add_u64 v[242:243], s[6:7], 0, v[132:133]
	global_load_lds_dwordx4 v130, s[96:97]
	s_mov_b32 m0, s23
	s_nop 0
	global_load_lds_dwordx4 v134, s[96:97]
	v_lshl_add_u64 v[240:241], s[6:7], 0, v[128:129]
	s_mov_b32 m0, s19
	s_nop 0
	global_load_lds_dwordx4 v[240:241], off
	s_mov_b32 m0, s24
	s_nop 0
	global_load_lds_dwordx4 v[242:243], off
	s_waitcnt vmcnt(8)
	s_waitcnt lgkmcnt(0)
	s_barrier
	s_setprio 1
	s_waitcnt lgkmcnt(0)
	v_mfma_f32_16x16x32_bf16 v[60:63], v[148:151], v[190:193], v[60:63]
	v_mfma_f32_16x16x32_bf16 v[56:59], v[156:159], v[190:193], v[56:59]
	v_mfma_f32_16x16x32_bf16 v[52:55], v[148:151], v[198:201], v[52:55]
	v_mfma_f32_16x16x32_bf16 v[48:51], v[156:159], v[198:201], v[48:51]
	v_mfma_f32_16x16x32_bf16 v[36:39], v[148:151], v[220:223], v[36:39]
	v_mfma_f32_16x16x32_bf16 v[32:35], v[156:159], v[220:223], v[32:35]
	v_mfma_f32_16x16x32_bf16 v[20:23], v[148:151], v[228:231], v[20:23]
	v_mfma_f32_16x16x32_bf16 v[16:19], v[156:159], v[228:231], v[16:19]
	v_mfma_f32_16x16x32_bf16 v[60:63], v[152:155], v[194:197], v[60:63]
	v_mfma_f32_16x16x32_bf16 v[56:59], v[160:163], v[194:197], v[56:59]
	v_mfma_f32_16x16x32_bf16 v[52:55], v[152:155], v[202:205], v[52:55]
	v_mfma_f32_16x16x32_bf16 v[48:51], v[160:163], v[202:205], v[48:51]
	v_mfma_f32_16x16x32_bf16 v[36:39], v[152:155], v[224:227], v[36:39]
	v_mfma_f32_16x16x32_bf16 v[32:35], v[160:163], v[224:227], v[32:35]
	v_mfma_f32_16x16x32_bf16 v[20:23], v[152:155], v[232:235], v[20:23]
	v_mfma_f32_16x16x32_bf16 v[16:19], v[160:163], v[232:235], v[16:19]
	s_setprio 0
	s_setprio 1
	v_mfma_f32_16x16x32_bf16 v[44:47], v[164:167], v[190:193], v[44:47]
	v_mfma_f32_16x16x32_bf16 v[40:43], v[172:175], v[190:193], v[40:43]
	v_mfma_f32_16x16x32_bf16 v[28:31], v[164:167], v[198:201], v[28:31]
	v_mfma_f32_16x16x32_bf16 v[24:27], v[172:175], v[198:201], v[24:27]
	v_mfma_f32_16x16x32_bf16 v[12:15], v[164:167], v[220:223], v[12:15]
	v_mfma_f32_16x16x32_bf16 v[8:11], v[172:175], v[220:223], v[8:11]
	v_mfma_f32_16x16x32_bf16 v[4:7], v[164:167], v[228:231], v[4:7]
	v_mfma_f32_16x16x32_bf16 v[0:3], v[172:175], v[228:231], v[0:3]
	v_mfma_f32_16x16x32_bf16 v[44:47], v[168:171], v[194:197], v[44:47]
	v_mfma_f32_16x16x32_bf16 v[40:43], v[186:189], v[194:197], v[40:43]
	v_mfma_f32_16x16x32_bf16 v[28:31], v[168:171], v[202:205], v[28:31]
	v_mfma_f32_16x16x32_bf16 v[24:27], v[186:189], v[202:205], v[24:27]
	v_mfma_f32_16x16x32_bf16 v[12:15], v[168:171], v[224:227], v[12:15]
	v_mfma_f32_16x16x32_bf16 v[8:11], v[186:189], v[224:227], v[8:11]
	v_mfma_f32_16x16x32_bf16 v[4:7], v[168:171], v[232:235], v[4:7]
	v_mfma_f32_16x16x32_bf16 v[0:3], v[186:189], v[232:235], v[0:3]
	s_setprio 0
	s_barrier
	v_or_b32_e32 v147, 0x18000, v145
	v_add_u32_e32 v152, 0x18400, v145
	ds_read_b128 v[148:151], v147
	ds_read_b128 v[152:155], v152
	v_add_u32_e32 v147, 0x18800, v145
	v_add_u32_e32 v160, 0x18c00, v145
	ds_read_b128 v[156:159], v147
	ds_read_b128 v[160:163], v160
	v_or_b32_e32 v147, 0x1c000, v145
	v_add_u32_e32 v168, 0x1c400, v145
	ds_read_b128 v[164:167], v147
	ds_read_b128 v[168:171], v168
	v_add_u32_e32 v147, 0x1c800, v145
	v_add_u32_e32 v186, 0x1cc00, v145
	ds_read_b128 v[172:175], v147
	ds_read_b128 v[186:189], v186
	s_add_u32 s6, s6, 0x40000
	s_addc_u32 s7, s7, 0
	s_mov_b32 m0, s25
	ds_read_b128 v[190:193], v144 offset:32768
	ds_read_b128 v[194:197], v144 offset:33792
	ds_read_b128 v[198:201], v144 offset:34816
	ds_read_b128 v[202:205], v144 offset:35840
	ds_read_b128 v[220:223], v144 offset:36864
	ds_read_b128 v[224:227], v144 offset:37888
	ds_read_b128 v[228:231], v144 offset:38912
	ds_read_b128 v[232:235], v144 offset:39936
	global_load_lds_dwordx4 v128, s[6:7]
	v_lshl_add_u64 v[244:245], s[6:7], 0, v[132:133]
	s_mov_b32 m0, s26
	s_nop 0
	global_load_lds_dwordx4 v[244:245], off
	s_waitcnt vmcnt(8)
	s_waitcnt lgkmcnt(0)
	s_barrier
	s_setprio 1
	s_waitcnt lgkmcnt(0)
	v_mfma_f32_16x16x32_bf16 v[124:127], v[148:151], v[190:193], v[124:127]
	v_mfma_f32_16x16x32_bf16 v[120:123], v[156:159], v[190:193], v[120:123]
	v_mfma_f32_16x16x32_bf16 v[116:119], v[148:151], v[198:201], v[116:119]
	v_mfma_f32_16x16x32_bf16 v[112:115], v[156:159], v[198:201], v[112:115]
	v_mfma_f32_16x16x32_bf16 v[100:103], v[148:151], v[220:223], v[100:103]
	v_mfma_f32_16x16x32_bf16 v[96:99], v[156:159], v[220:223], v[96:99]
	v_mfma_f32_16x16x32_bf16 v[84:87], v[148:151], v[228:231], v[84:87]
	v_mfma_f32_16x16x32_bf16 v[80:83], v[156:159], v[228:231], v[80:83]
	v_mfma_f32_16x16x32_bf16 v[124:127], v[152:155], v[194:197], v[124:127]
	v_mfma_f32_16x16x32_bf16 v[120:123], v[160:163], v[194:197], v[120:123]
	v_mfma_f32_16x16x32_bf16 v[116:119], v[152:155], v[202:205], v[116:119]
	v_mfma_f32_16x16x32_bf16 v[112:115], v[160:163], v[202:205], v[112:115]
	v_mfma_f32_16x16x32_bf16 v[100:103], v[152:155], v[224:227], v[100:103]
	v_mfma_f32_16x16x32_bf16 v[96:99], v[160:163], v[224:227], v[96:99]
	v_mfma_f32_16x16x32_bf16 v[84:87], v[152:155], v[232:235], v[84:87]
	v_mfma_f32_16x16x32_bf16 v[80:83], v[160:163], v[232:235], v[80:83]
	s_setprio 0
	s_setprio 1
	v_mfma_f32_16x16x32_bf16 v[108:111], v[164:167], v[190:193], v[108:111]
	v_mfma_f32_16x16x32_bf16 v[104:107], v[172:175], v[190:193], v[104:107]
	v_mfma_f32_16x16x32_bf16 v[92:95], v[164:167], v[198:201], v[92:95]
	v_mfma_f32_16x16x32_bf16 v[88:91], v[172:175], v[198:201], v[88:91]
	v_mfma_f32_16x16x32_bf16 v[76:79], v[164:167], v[220:223], v[76:79]
	v_mfma_f32_16x16x32_bf16 v[72:75], v[172:175], v[220:223], v[72:75]
	v_mfma_f32_16x16x32_bf16 v[68:71], v[164:167], v[228:231], v[68:71]
	v_mfma_f32_16x16x32_bf16 v[64:67], v[172:175], v[228:231], v[64:67]
	v_mfma_f32_16x16x32_bf16 v[108:111], v[168:171], v[194:197], v[108:111]
	v_mfma_f32_16x16x32_bf16 v[104:107], v[186:189], v[194:197], v[104:107]
	v_mfma_f32_16x16x32_bf16 v[92:95], v[168:171], v[202:205], v[92:95]
	v_mfma_f32_16x16x32_bf16 v[88:91], v[186:189], v[202:205], v[88:91]
	v_mfma_f32_16x16x32_bf16 v[76:79], v[168:171], v[224:227], v[76:79]
	v_mfma_f32_16x16x32_bf16 v[72:75], v[186:189], v[224:227], v[72:75]
	v_mfma_f32_16x16x32_bf16 v[68:71], v[168:171], v[232:235], v[68:71]
	v_mfma_f32_16x16x32_bf16 v[64:67], v[186:189], v[232:235], v[64:67]
	s_setprio 0
	s_barrier
	s_mov_b32 m0, s27
	v_lshl_add_u64 v[236:237], v[236:237], 0, s[0:1]
	s_add_u32 s2, s2, 0x40080
	ds_read_b128 v[190:193], v144 offset:49152
	ds_read_b128 v[194:197], v144 offset:50176
	ds_read_b128 v[198:201], v144 offset:51200
	ds_read_b128 v[202:205], v144 offset:52224
	ds_read_b128 v[220:223], v144 offset:53248
	ds_read_b128 v[224:227], v144 offset:54272
	ds_read_b128 v[228:231], v144 offset:55296
	ds_read_b128 v[232:235], v144 offset:56320
	global_load_lds_dwordx4 v[236:237], off
	v_lshl_add_u64 v[236:237], v[238:239], 0, s[0:1]
	s_mov_b32 m0, s28
	s_addc_u32 s3, s3, 0
	global_load_lds_dwordx4 v[236:237], off
	s_mov_b32 m0, s31
	s_nop 0
	global_load_lds_dwordx4 v130, s[2:3]
	s_mov_b32 m0, s34
	s_nop 0
	global_load_lds_dwordx4 v134, s[2:3]
	v_lshl_add_u64 v[236:237], v[240:241], 0, s[0:1]
	s_mov_b32 m0, s29
	s_nop 0
	global_load_lds_dwordx4 v[236:237], off
	v_lshl_add_u64 v[236:237], v[242:243], 0, s[0:1]
	s_mov_b32 m0, s30
	s_nop 0
	global_load_lds_dwordx4 v[236:237], off
	s_waitcnt vmcnt(8)
	s_waitcnt lgkmcnt(0)
	s_barrier
	s_setprio 1
	s_waitcnt lgkmcnt(0)
	v_mfma_f32_16x16x32_bf16 v[60:63], v[148:151], v[190:193], v[60:63]
	v_mfma_f32_16x16x32_bf16 v[56:59], v[156:159], v[190:193], v[56:59]
	v_mfma_f32_16x16x32_bf16 v[52:55], v[148:151], v[198:201], v[52:55]
	v_mfma_f32_16x16x32_bf16 v[48:51], v[156:159], v[198:201], v[48:51]
	v_mfma_f32_16x16x32_bf16 v[36:39], v[148:151], v[220:223], v[36:39]
	v_mfma_f32_16x16x32_bf16 v[32:35], v[156:159], v[220:223], v[32:35]
	v_mfma_f32_16x16x32_bf16 v[20:23], v[148:151], v[228:231], v[20:23]
	v_mfma_f32_16x16x32_bf16 v[16:19], v[156:159], v[228:231], v[16:19]
	v_mfma_f32_16x16x32_bf16 v[60:63], v[152:155], v[194:197], v[60:63]
	v_mfma_f32_16x16x32_bf16 v[56:59], v[160:163], v[194:197], v[56:59]
	v_mfma_f32_16x16x32_bf16 v[52:55], v[152:155], v[202:205], v[52:55]
	v_mfma_f32_16x16x32_bf16 v[48:51], v[160:163], v[202:205], v[48:51]
	v_mfma_f32_16x16x32_bf16 v[36:39], v[152:155], v[224:227], v[36:39]
	v_mfma_f32_16x16x32_bf16 v[32:35], v[160:163], v[224:227], v[32:35]
	v_mfma_f32_16x16x32_bf16 v[20:23], v[152:155], v[232:235], v[20:23]
	v_mfma_f32_16x16x32_bf16 v[16:19], v[160:163], v[232:235], v[16:19]
	s_setprio 0
	s_setprio 1
	v_mfma_f32_16x16x32_bf16 v[44:47], v[164:167], v[190:193], v[44:47]
	v_mfma_f32_16x16x32_bf16 v[40:43], v[172:175], v[190:193], v[40:43]
	v_mfma_f32_16x16x32_bf16 v[28:31], v[164:167], v[198:201], v[28:31]
	v_mfma_f32_16x16x32_bf16 v[24:27], v[172:175], v[198:201], v[24:27]
	v_mfma_f32_16x16x32_bf16 v[12:15], v[164:167], v[220:223], v[12:15]
	v_mfma_f32_16x16x32_bf16 v[8:11], v[172:175], v[220:223], v[8:11]
	v_mfma_f32_16x16x32_bf16 v[4:7], v[164:167], v[228:231], v[4:7]
	v_mfma_f32_16x16x32_bf16 v[0:3], v[172:175], v[228:231], v[0:3]
	v_mfma_f32_16x16x32_bf16 v[44:47], v[168:171], v[194:197], v[44:47]
	v_mfma_f32_16x16x32_bf16 v[40:43], v[186:189], v[194:197], v[40:43]
	v_mfma_f32_16x16x32_bf16 v[28:31], v[168:171], v[202:205], v[28:31]
	v_mfma_f32_16x16x32_bf16 v[24:27], v[186:189], v[202:205], v[24:27]
	v_mfma_f32_16x16x32_bf16 v[12:15], v[168:171], v[224:227], v[12:15]
	v_mfma_f32_16x16x32_bf16 v[8:11], v[186:189], v[224:227], v[8:11]
	v_mfma_f32_16x16x32_bf16 v[4:7], v[168:171], v[232:235], v[4:7]
	v_mfma_f32_16x16x32_bf16 v[0:3], v[186:189], v[232:235], v[0:3]
	s_setprio 0
	s_barrier
	s_add_i32 s95, s95, 2
	s_add_u32 s90, s90, 0x100
	s_addc_u32 s91, s91, 0
	s_add_u32 s92, s92, 0x100
	s_addc_u32 s94, s94, 0
	s_cmp_gt_u32 s95, 13
	s_cbranch_scc0 .LBB0_462
	s_and_b64 vcc, exec, s[40:41]
	s_cbranch_vccz .LBB0_465
	s_barrier
